# SwiGLU epilogue: rstd^2 folded into the reciprocal (d = fma(e, x, x) with x = mean+eps), drops 5 more VALU ops per 16-acc group
# baseline (speedup 1.0000x reference)
; __device__ __forceinline__ unsigned cvtpk(float lo, float hi) { f32x2v_ v = {lo, hi}; bf16x2v_ b = __builtin_convertvector(v, bf16x2v_); return __builtin_bit_cast(unsigned, b); }
; __device__ __forceinline__ float row_rs(const float* ssp, int row) { const unsigned long long v = ((const unsigned long long*)ssp)[row];
;     return __builtin_amdgcn_rsqf((float)v * (1.0f / 4294967296.0f) * (1.0f / 1024.0f) + RMS_EPS); }
;     __device__ __forceinline__ void operator()(const f32x4 (&acc)[2][2][4][2], const Unit& u, int wr, int wc, int fr, int fq) const {
;     ...
;             for (int m = 0; m < 4; ++m) { const int row = row0 + ai * HALF + m * 16; const float rs = row_rs(ss, row);
;                 float hv[8];
; #pragma unroll
;                 for (int n = 0; n < 2; ++n)
; #pragma unroll
;                     for (int i = 0; i < 4; ++i) { const float g = acc[ai][0][m][n][i] * rs, uu = acc[ai][1][m][n][i] * rs;
;                         hv[n * 4 + i] = g * __builtin_amdgcn_rcpf(1.0f + __expf(-g)) * uu; }
;                 u32x4 w; w.x = cvtpk(hv[0], hv[1]); w.y = cvtpk(hv[2], hv[3]); w.z = cvtpk(hv[4], hv[5]); w.w = cvtpk(hv[6], hv[7]);
;                 *(u32x4*)(H + (size_t)row * ldh + col0) = w; }
.LBB0_194:
	v_lshl_or_b32 v160, s66, 7, v154
	v_ashrrev_i32_e32 v161, 31, v160
	v_or_b32_e32 v164, 16, v144
	v_ashrrev_i32_e32 v165, 31, v164
	v_lshl_add_u64 v[168:169], v[164:165], 3, s[6:7]
	v_mov_b64_e32 v[146:147], s[20:21]
	v_mad_i64_i32 v[162:163], s[14:15], v144, s65, v[146:147]
	s_andn2_b64 vcc, exec, s[0:1]
	s_mov_b64 s[0:1], -1
	s_waitcnt vmcnt(7)
	v_cvt_f32_u32_e32 v159, v183
	v_cvt_f32_u32_e32 v145, v182
	v_lshlrev_b64 v[148:149], 1, v[160:161]
	v_lshl_add_u64 v[162:163], v[162:163], 0, v[148:149]
	v_fmamk_f32 v145, v145, 0x2f800000, v159
	v_fmamk_f32 v183, v145, 0x3a800000, v158
	v_rsq_f32_e32 v160, v183
	s_nop 0
	v_mul_f32_e32 v182, 0xbfb8aa3b, v160
	v_pk_mul_f32 v[160:161], v[124:125], v[182:183] op_sel_hi:[1,0]
	v_pk_mul_f32 v[170:171], v[126:127], v[182:183] op_sel_hi:[1,0]
	v_pk_mul_f32 v[172:173], v[120:121], v[182:183] op_sel_hi:[1,0]
	v_pk_mul_f32 v[174:175], v[122:123], v[182:183] op_sel_hi:[1,0]
	v_pk_mul_f32 v[116:117], v[116:117], v[124:125]
	v_pk_mul_f32 v[118:119], v[118:119], v[126:127]
	v_pk_mul_f32 v[120:121], v[112:113], v[120:121]
	v_pk_mul_f32 v[122:123], v[114:115], v[122:123]
	v_exp_f32_e32 v160, v160
	v_exp_f32_e32 v161, v161
	v_exp_f32_e32 v170, v170
	v_exp_f32_e32 v171, v171
	v_exp_f32_e32 v172, v172
	v_exp_f32_e32 v173, v173
	v_exp_f32_e32 v174, v174
	v_exp_f32_e32 v175, v175
	v_pk_fma_f32 v[160:161], v[160:161], v[182:183], v[182:183] op_sel:[0,1,1] op_sel_hi:[1,1,1]
	v_pk_fma_f32 v[170:171], v[170:171], v[182:183], v[182:183] op_sel:[0,1,1] op_sel_hi:[1,1,1]
	v_pk_fma_f32 v[172:173], v[172:173], v[182:183], v[182:183] op_sel:[0,1,1] op_sel_hi:[1,1,1]
	v_pk_fma_f32 v[174:175], v[174:175], v[182:183], v[182:183] op_sel:[0,1,1] op_sel_hi:[1,1,1]
	v_rcp_f32_e32 v160, v160
	v_rcp_f32_e32 v161, v161
	v_rcp_f32_e32 v170, v170
	v_rcp_f32_e32 v171, v171
	v_rcp_f32_e32 v172, v172
	v_rcp_f32_e32 v173, v173
	v_rcp_f32_e32 v174, v174
	v_rcp_f32_e32 v175, v175
	v_pk_mul_f32 v[116:117], v[116:117], v[160:161]
	v_pk_mul_f32 v[118:119], v[118:119], v[170:171]
	v_pk_mul_f32 v[120:121], v[120:121], v[172:173]
	v_pk_mul_f32 v[122:123], v[122:123], v[174:175]
	v_cvt_pk_bf16_f32 v112, v116, v117
	v_cvt_pk_bf16_f32 v113, v118, v119
	v_cvt_pk_bf16_f32 v114, v120, v121
	v_cvt_pk_bf16_f32 v115, v122, v123
	global_store_dwordx4 v[162:163], v[112:115], off
	s_nop 0
	s_nop 0
	v_or_b32_e32 v114, 32, v144
	s_waitcnt vmcnt(7)
	v_cvt_f32_u32_e32 v116, v185
	v_cvt_f32_u32_e32 v115, v184
	v_mad_i64_i32 v[112:113], s[14:15], v164, s65, v[146:147]
	v_fmamk_f32 v115, v115, 0x2f800000, v116
	v_fmamk_f32 v185, v115, 0x3a800000, v158
	v_rsq_f32_e32 v116, v185
	v_ashrrev_i32_e32 v115, 31, v114
	v_lshl_add_u64 v[118:119], v[114:115], 3, s[6:7]
	v_lshl_add_u64 v[112:113], v[112:113], 0, v[148:149]
	v_mul_f32_e32 v184, 0xbfb8aa3b, v116
	v_pk_mul_f32 v[116:117], v[108:109], v[184:185] op_sel_hi:[1,0]
	v_pk_mul_f32 v[120:121], v[110:111], v[184:185] op_sel_hi:[1,0]
	v_pk_mul_f32 v[122:123], v[104:105], v[184:185] op_sel_hi:[1,0]
	v_pk_mul_f32 v[124:125], v[106:107], v[184:185] op_sel_hi:[1,0]
	v_pk_mul_f32 v[100:101], v[100:101], v[108:109]
	v_pk_mul_f32 v[102:103], v[102:103], v[110:111]
	v_pk_mul_f32 v[104:105], v[96:97], v[104:105]
	v_pk_mul_f32 v[106:107], v[98:99], v[106:107]
	v_exp_f32_e32 v116, v116
	v_exp_f32_e32 v117, v117
	v_exp_f32_e32 v120, v120
	v_exp_f32_e32 v121, v121
	v_exp_f32_e32 v122, v122
	v_exp_f32_e32 v123, v123
	v_exp_f32_e32 v124, v124
	v_exp_f32_e32 v125, v125
	v_pk_fma_f32 v[116:117], v[116:117], v[184:185], v[184:185] op_sel:[0,1,1] op_sel_hi:[1,1,1]
	v_pk_fma_f32 v[120:121], v[120:121], v[184:185], v[184:185] op_sel:[0,1,1] op_sel_hi:[1,1,1]
	v_pk_fma_f32 v[122:123], v[122:123], v[184:185], v[184:185] op_sel:[0,1,1] op_sel_hi:[1,1,1]
	v_pk_fma_f32 v[124:125], v[124:125], v[184:185], v[184:185] op_sel:[0,1,1] op_sel_hi:[1,1,1]
	v_rcp_f32_e32 v116, v116
	v_rcp_f32_e32 v117, v117
	v_rcp_f32_e32 v120, v120
	v_rcp_f32_e32 v121, v121
	v_rcp_f32_e32 v122, v122
	v_rcp_f32_e32 v123, v123
	v_rcp_f32_e32 v124, v124
	v_rcp_f32_e32 v125, v125
	v_pk_mul_f32 v[100:101], v[100:101], v[116:117]
	v_pk_mul_f32 v[102:103], v[102:103], v[120:121]
	v_pk_mul_f32 v[104:105], v[104:105], v[122:123]
	v_pk_mul_f32 v[106:107], v[106:107], v[124:125]
	v_cvt_pk_bf16_f32 v96, v100, v101
	v_cvt_pk_bf16_f32 v97, v102, v103
	v_cvt_pk_bf16_f32 v98, v104, v105
	v_cvt_pk_bf16_f32 v99, v106, v107
	global_store_dwordx4 v[112:113], v[96:99], off
	s_nop 0
	s_nop 0
	v_or_b32_e32 v98, 48, v144
	s_waitcnt vmcnt(7)
	v_cvt_f32_u32_e32 v100, v187
	v_cvt_f32_u32_e32 v99, v186
	v_mad_i64_i32 v[96:97], s[14:15], v114, s65, v[146:147]
	v_fmamk_f32 v99, v99, 0x2f800000, v100
	v_fmamk_f32 v187, v99, 0x3a800000, v158
	v_rsq_f32_e32 v100, v187
	v_ashrrev_i32_e32 v99, 31, v98
	v_lshl_add_u64 v[102:103], v[98:99], 3, s[6:7]
	v_lshl_add_u64 v[96:97], v[96:97], 0, v[148:149]
	v_mul_f32_e32 v186, 0xbfb8aa3b, v100
	v_pk_mul_f32 v[100:101], v[92:93], v[186:187] op_sel_hi:[1,0]
	v_pk_mul_f32 v[104:105], v[94:95], v[186:187] op_sel_hi:[1,0]
	v_pk_mul_f32 v[106:107], v[88:89], v[186:187] op_sel_hi:[1,0]
	v_pk_mul_f32 v[108:109], v[90:91], v[186:187] op_sel_hi:[1,0]
	v_pk_mul_f32 v[84:85], v[84:85], v[92:93]
	v_pk_mul_f32 v[86:87], v[86:87], v[94:95]
	v_pk_mul_f32 v[88:89], v[80:81], v[88:89]
	v_pk_mul_f32 v[90:91], v[82:83], v[90:91]
	v_exp_f32_e32 v100, v100
	v_exp_f32_e32 v101, v101
	v_exp_f32_e32 v104, v104
	v_exp_f32_e32 v105, v105
	v_exp_f32_e32 v106, v106
	v_exp_f32_e32 v107, v107
	v_exp_f32_e32 v108, v108
	v_exp_f32_e32 v109, v109
	v_pk_fma_f32 v[100:101], v[100:101], v[186:187], v[186:187] op_sel:[0,1,1] op_sel_hi:[1,1,1]
	v_pk_fma_f32 v[104:105], v[104:105], v[186:187], v[186:187] op_sel:[0,1,1] op_sel_hi:[1,1,1]
	v_pk_fma_f32 v[106:107], v[106:107], v[186:187], v[186:187] op_sel:[0,1,1] op_sel_hi:[1,1,1]
	v_pk_fma_f32 v[108:109], v[108:109], v[186:187], v[186:187] op_sel:[0,1,1] op_sel_hi:[1,1,1]
	v_rcp_f32_e32 v100, v100
	v_rcp_f32_e32 v101, v101
	v_rcp_f32_e32 v104, v104
	v_rcp_f32_e32 v105, v105
	v_rcp_f32_e32 v106, v106
	v_rcp_f32_e32 v107, v107
	v_rcp_f32_e32 v108, v108
	v_rcp_f32_e32 v109, v109
	v_pk_mul_f32 v[84:85], v[84:85], v[100:101]
	v_pk_mul_f32 v[86:87], v[86:87], v[104:105]
	v_pk_mul_f32 v[88:89], v[88:89], v[106:107]
	v_pk_mul_f32 v[90:91], v[90:91], v[108:109]
	v_cvt_pk_bf16_f32 v80, v84, v85
	v_cvt_pk_bf16_f32 v81, v86, v87
	v_cvt_pk_bf16_f32 v82, v88, v89
	v_cvt_pk_bf16_f32 v83, v90, v91
	global_store_dwordx4 v[96:97], v[80:83], off
	s_nop 0
	s_waitcnt vmcnt(7)
; __device__ __forceinline__ unsigned cvtpk(float lo, float hi) { f32x2v_ v = {lo, hi}; bf16x2v_ b = __builtin_convertvector(v, bf16x2v_); return __builtin_bit_cast(unsigned, b); }
; __device__ __forceinline__ float row_rs(const float* ssp, int row) { const unsigned long long v = ((const unsigned long long*)ssp)[row];
;     return __builtin_amdgcn_rsqf((float)v * (1.0f / 4294967296.0f) * (1.0f / 1024.0f) + RMS_EPS); }
;     __device__ __forceinline__ void operator()(const f32x4 (&acc)[2][2][4][2], const Unit& u, int wr, int wc, int fr, int fq) const {
;     ...
;             for (int m = 0; m < 4; ++m) { const int row = row0 + ai * HALF + m * 16; const float rs = row_rs(ss, row);
;                 float hv[8];
; #pragma unroll
;                 for (int n = 0; n < 2; ++n)
; #pragma unroll
;                     for (int i = 0; i < 4; ++i) { const float g = acc[ai][0][m][n][i] * rs, uu = acc[ai][1][m][n][i] * rs;
;                         hv[n * 4 + i] = g * __builtin_amdgcn_rcpf(1.0f + __expf(-g)) * uu; }
;                 u32x4 w; w.x = cvtpk(hv[0], hv[1]); w.y = cvtpk(hv[2], hv[3]); w.z = cvtpk(hv[4], hv[5]); w.w = cvtpk(hv[6], hv[7]);
;                 *(u32x4*)(H + (size_t)row * ldh + col0) = w; }
	v_cvt_f32_u32_e32 v80, v189
	v_cvt_f32_u32_e32 v81, v188
	v_mad_i64_i32 v[82:83], s[14:15], v98, s65, v[146:147]
	v_fmamk_f32 v80, v81, 0x2f800000, v80
	v_fmamk_f32 v189, v80, 0x3a800000, v158
	v_rsq_f32_e32 v80, v189
	v_lshl_add_u64 v[82:83], v[82:83], 0, v[148:149]
	v_mul_f32_e32 v188, 0xbfb8aa3b, v80
	v_pk_mul_f32 v[80:81], v[76:77], v[188:189] op_sel_hi:[1,0]
	v_pk_mul_f32 v[84:85], v[78:79], v[188:189] op_sel_hi:[1,0]
	v_pk_mul_f32 v[86:87], v[72:73], v[188:189] op_sel_hi:[1,0]
	v_pk_mul_f32 v[88:89], v[74:75], v[188:189] op_sel_hi:[1,0]
	v_pk_mul_f32 v[68:69], v[68:69], v[76:77]
	v_pk_mul_f32 v[70:71], v[70:71], v[78:79]
	v_pk_mul_f32 v[72:73], v[64:65], v[72:73]
	v_pk_mul_f32 v[74:75], v[66:67], v[74:75]
	v_exp_f32_e32 v80, v80
	v_exp_f32_e32 v81, v81
	v_exp_f32_e32 v84, v84
	v_exp_f32_e32 v85, v85
	v_exp_f32_e32 v86, v86
	v_exp_f32_e32 v87, v87
	v_exp_f32_e32 v88, v88
	v_exp_f32_e32 v89, v89
	v_pk_fma_f32 v[80:81], v[80:81], v[188:189], v[188:189] op_sel:[0,1,1] op_sel_hi:[1,1,1]
	v_pk_fma_f32 v[84:85], v[84:85], v[188:189], v[188:189] op_sel:[0,1,1] op_sel_hi:[1,1,1]
	v_pk_fma_f32 v[86:87], v[86:87], v[188:189], v[188:189] op_sel:[0,1,1] op_sel_hi:[1,1,1]
	v_pk_fma_f32 v[88:89], v[88:89], v[188:189], v[188:189] op_sel:[0,1,1] op_sel_hi:[1,1,1]
	v_rcp_f32_e32 v80, v80
	v_rcp_f32_e32 v81, v81
	v_rcp_f32_e32 v84, v84
	v_rcp_f32_e32 v85, v85
	v_rcp_f32_e32 v86, v86
	v_rcp_f32_e32 v87, v87
	v_rcp_f32_e32 v88, v88
	v_rcp_f32_e32 v89, v89
	v_pk_mul_f32 v[68:69], v[68:69], v[80:81]
	v_pk_mul_f32 v[70:71], v[70:71], v[84:85]
	v_pk_mul_f32 v[72:73], v[72:73], v[86:87]
	v_pk_mul_f32 v[74:75], v[74:75], v[88:89]
	v_cvt_pk_bf16_f32 v64, v68, v69
	v_cvt_pk_bf16_f32 v65, v70, v71
	v_cvt_pk_bf16_f32 v66, v72, v73
	v_cvt_pk_bf16_f32 v67, v74, v75
	global_store_dwordx4 v[82:83], v[64:67], off
	s_nop 0
	s_waitcnt vmcnt(7)
	v_cvt_f32_u32_e32 v64, v191
	v_cvt_f32_u32_e32 v66, v190
	v_add_u32_e32 v65, 0x80, v144
	v_fmamk_f32 v64, v66, 0x2f800000, v64
	v_fmamk_f32 v191, v64, 0x3a800000, v158
	v_rsq_f32_e32 v64, v191
	v_mad_i64_i32 v[66:67], s[14:15], v65, s65, v[146:147]
	v_lshl_add_u64 v[66:67], v[66:67], 0, v[148:149]
	v_mul_f32_e32 v190, 0xbfb8aa3b, v64
	v_pk_mul_f32 v[64:65], v[60:61], v[190:191] op_sel_hi:[1,0]
	v_pk_mul_f32 v[68:69], v[62:63], v[190:191] op_sel_hi:[1,0]
	v_pk_mul_f32 v[70:71], v[56:57], v[190:191] op_sel_hi:[1,0]
	v_pk_mul_f32 v[72:73], v[58:59], v[190:191] op_sel_hi:[1,0]
	v_pk_mul_f32 v[52:53], v[52:53], v[60:61]
	v_pk_mul_f32 v[54:55], v[54:55], v[62:63]
	v_pk_mul_f32 v[56:57], v[48:49], v[56:57]
	v_pk_mul_f32 v[58:59], v[50:51], v[58:59]
	v_exp_f32_e32 v64, v64
	v_exp_f32_e32 v65, v65
	v_exp_f32_e32 v68, v68
	v_exp_f32_e32 v69, v69
	v_exp_f32_e32 v70, v70
	v_exp_f32_e32 v71, v71
	v_exp_f32_e32 v72, v72
	v_exp_f32_e32 v73, v73
	v_pk_fma_f32 v[64:65], v[64:65], v[190:191], v[190:191] op_sel:[0,1,1] op_sel_hi:[1,1,1]
	v_pk_fma_f32 v[68:69], v[68:69], v[190:191], v[190:191] op_sel:[0,1,1] op_sel_hi:[1,1,1]
	v_pk_fma_f32 v[70:71], v[70:71], v[190:191], v[190:191] op_sel:[0,1,1] op_sel_hi:[1,1,1]
	v_pk_fma_f32 v[72:73], v[72:73], v[190:191], v[190:191] op_sel:[0,1,1] op_sel_hi:[1,1,1]
	v_rcp_f32_e32 v64, v64
	v_rcp_f32_e32 v65, v65
	v_rcp_f32_e32 v68, v68
	v_rcp_f32_e32 v69, v69
	v_rcp_f32_e32 v70, v70
	v_rcp_f32_e32 v71, v71
	v_rcp_f32_e32 v72, v72
	v_rcp_f32_e32 v73, v73
	v_pk_mul_f32 v[52:53], v[52:53], v[64:65]
	v_pk_mul_f32 v[54:55], v[54:55], v[68:69]
	v_pk_mul_f32 v[56:57], v[56:57], v[70:71]
	v_pk_mul_f32 v[58:59], v[58:59], v[72:73]
	v_cvt_pk_bf16_f32 v48, v52, v53
	v_cvt_pk_bf16_f32 v49, v54, v55
	v_cvt_pk_bf16_f32 v50, v56, v57
	v_cvt_pk_bf16_f32 v51, v58, v59
	global_store_dwordx4 v[66:67], v[48:51], off
	s_nop 0
	s_waitcnt vmcnt(7)
	v_cvt_f32_u32_e32 v48, v193
	v_cvt_f32_u32_e32 v50, v192
	v_add_u32_e32 v49, 0x90, v144
	v_fmamk_f32 v48, v50, 0x2f800000, v48
	v_fmamk_f32 v193, v48, 0x3a800000, v158
	v_rsq_f32_e32 v48, v193
	v_mad_i64_i32 v[50:51], s[14:15], v49, s65, v[146:147]
	v_lshl_add_u64 v[50:51], v[50:51], 0, v[148:149]
	v_mul_f32_e32 v192, 0xbfb8aa3b, v48
	v_pk_mul_f32 v[48:49], v[44:45], v[192:193] op_sel_hi:[1,0]
	v_pk_mul_f32 v[52:53], v[46:47], v[192:193] op_sel_hi:[1,0]
	v_pk_mul_f32 v[54:55], v[40:41], v[192:193] op_sel_hi:[1,0]
	v_pk_mul_f32 v[56:57], v[42:43], v[192:193] op_sel_hi:[1,0]
	v_pk_mul_f32 v[36:37], v[36:37], v[44:45]
	v_pk_mul_f32 v[38:39], v[38:39], v[46:47]
	v_pk_mul_f32 v[40:41], v[32:33], v[40:41]
	v_pk_mul_f32 v[42:43], v[34:35], v[42:43]
	v_exp_f32_e32 v48, v48
	v_exp_f32_e32 v49, v49
	v_exp_f32_e32 v52, v52
	v_exp_f32_e32 v53, v53
	v_exp_f32_e32 v54, v54
	v_exp_f32_e32 v55, v55
	v_exp_f32_e32 v56, v56
	v_exp_f32_e32 v57, v57
	v_pk_fma_f32 v[48:49], v[48:49], v[192:193], v[192:193] op_sel:[0,1,1] op_sel_hi:[1,1,1]
	v_pk_fma_f32 v[52:53], v[52:53], v[192:193], v[192:193] op_sel:[0,1,1] op_sel_hi:[1,1,1]
	v_pk_fma_f32 v[54:55], v[54:55], v[192:193], v[192:193] op_sel:[0,1,1] op_sel_hi:[1,1,1]
	v_pk_fma_f32 v[56:57], v[56:57], v[192:193], v[192:193] op_sel:[0,1,1] op_sel_hi:[1,1,1]
	v_rcp_f32_e32 v48, v48
	v_rcp_f32_e32 v49, v49
	v_rcp_f32_e32 v52, v52
	v_rcp_f32_e32 v53, v53
	v_rcp_f32_e32 v54, v54
	v_rcp_f32_e32 v55, v55
	v_rcp_f32_e32 v56, v56
	v_rcp_f32_e32 v57, v57
	v_pk_mul_f32 v[36:37], v[36:37], v[48:49]
	v_pk_mul_f32 v[38:39], v[38:39], v[52:53]
	v_pk_mul_f32 v[40:41], v[40:41], v[54:55]
	v_pk_mul_f32 v[42:43], v[42:43], v[56:57]
	v_cvt_pk_bf16_f32 v32, v36, v37
	v_cvt_pk_bf16_f32 v33, v38, v39
	v_cvt_pk_bf16_f32 v34, v40, v41
	v_cvt_pk_bf16_f32 v35, v42, v43
	global_store_dwordx4 v[50:51], v[32:35], off
	s_nop 0
	s_waitcnt vmcnt(7)
; __device__ __forceinline__ unsigned cvtpk(float lo, float hi) { f32x2v_ v = {lo, hi}; bf16x2v_ b = __builtin_convertvector(v, bf16x2v_); return __builtin_bit_cast(unsigned, b); }
; __device__ __forceinline__ float row_rs(const float* ssp, int row) { const unsigned long long v = ((const unsigned long long*)ssp)[row];
;     return __builtin_amdgcn_rsqf((float)v * (1.0f / 4294967296.0f) * (1.0f / 1024.0f) + RMS_EPS); }
;     __device__ __forceinline__ void operator()(const f32x4 (&acc)[2][2][4][2], const Unit& u, int wr, int wc, int fr, int fq) const {
;     ...
;             for (int m = 0; m < 4; ++m) { const int row = row0 + ai * HALF + m * 16; const float rs = row_rs(ss, row);
;                 float hv[8];
; #pragma unroll
;                 for (int n = 0; n < 2; ++n)
; #pragma unroll
;                     for (int i = 0; i < 4; ++i) { const float g = acc[ai][0][m][n][i] * rs, uu = acc[ai][1][m][n][i] * rs;
;                         hv[n * 4 + i] = g * __builtin_amdgcn_rcpf(1.0f + __expf(-g)) * uu; }
;                 u32x4 w; w.x = cvtpk(hv[0], hv[1]); w.y = cvtpk(hv[2], hv[3]); w.z = cvtpk(hv[4], hv[5]); w.w = cvtpk(hv[6], hv[7]);
;                 *(u32x4*)(H + (size_t)row * ldh + col0) = w; }
	v_cvt_f32_u32_e32 v32, v195
	v_cvt_f32_u32_e32 v34, v194
	v_add_u32_e32 v33, 0xa0, v144
	v_fmamk_f32 v32, v34, 0x2f800000, v32
	v_fmamk_f32 v195, v32, 0x3a800000, v158
	v_rsq_f32_e32 v32, v195
	v_mad_i64_i32 v[34:35], s[14:15], v33, s65, v[146:147]
	v_lshl_add_u64 v[34:35], v[34:35], 0, v[148:149]
	v_mul_f32_e32 v194, 0xbfb8aa3b, v32
	v_pk_mul_f32 v[32:33], v[28:29], v[194:195] op_sel_hi:[1,0]
	v_pk_mul_f32 v[36:37], v[30:31], v[194:195] op_sel_hi:[1,0]
	v_pk_mul_f32 v[38:39], v[24:25], v[194:195] op_sel_hi:[1,0]
	v_pk_mul_f32 v[40:41], v[26:27], v[194:195] op_sel_hi:[1,0]
	v_pk_mul_f32 v[20:21], v[20:21], v[28:29]
	v_pk_mul_f32 v[22:23], v[22:23], v[30:31]
	v_pk_mul_f32 v[24:25], v[16:17], v[24:25]
	v_pk_mul_f32 v[26:27], v[18:19], v[26:27]
	v_exp_f32_e32 v32, v32
	v_exp_f32_e32 v33, v33
	v_exp_f32_e32 v36, v36
	v_exp_f32_e32 v37, v37
	v_exp_f32_e32 v38, v38
	v_exp_f32_e32 v39, v39
	v_exp_f32_e32 v40, v40
	v_exp_f32_e32 v41, v41
	v_pk_fma_f32 v[32:33], v[32:33], v[194:195], v[194:195] op_sel:[0,1,1] op_sel_hi:[1,1,1]
	v_pk_fma_f32 v[36:37], v[36:37], v[194:195], v[194:195] op_sel:[0,1,1] op_sel_hi:[1,1,1]
	v_pk_fma_f32 v[38:39], v[38:39], v[194:195], v[194:195] op_sel:[0,1,1] op_sel_hi:[1,1,1]
	v_pk_fma_f32 v[40:41], v[40:41], v[194:195], v[194:195] op_sel:[0,1,1] op_sel_hi:[1,1,1]
	v_rcp_f32_e32 v32, v32
	v_rcp_f32_e32 v33, v33
	v_rcp_f32_e32 v36, v36
	v_rcp_f32_e32 v37, v37
	v_rcp_f32_e32 v38, v38
	v_rcp_f32_e32 v39, v39
	v_rcp_f32_e32 v40, v40
	v_rcp_f32_e32 v41, v41
	v_pk_mul_f32 v[20:21], v[20:21], v[32:33]
	v_pk_mul_f32 v[22:23], v[22:23], v[36:37]
	v_pk_mul_f32 v[24:25], v[24:25], v[38:39]
	v_pk_mul_f32 v[26:27], v[26:27], v[40:41]
	v_cvt_pk_bf16_f32 v16, v20, v21
	v_cvt_pk_bf16_f32 v17, v22, v23
	v_cvt_pk_bf16_f32 v18, v24, v25
	v_cvt_pk_bf16_f32 v19, v26, v27
	global_store_dwordx4 v[34:35], v[16:19], off
	s_nop 0
	s_waitcnt vmcnt(7)
	v_cvt_f32_u32_e32 v16, v197
	v_cvt_f32_u32_e32 v18, v196
	v_add_u32_e32 v17, 0xb0, v144
	v_fmamk_f32 v16, v18, 0x2f800000, v16
	v_fmamk_f32 v197, v16, 0x3a800000, v158
	v_rsq_f32_e32 v16, v197
	v_mad_i64_i32 v[18:19], s[14:15], v17, s65, v[146:147]
	v_lshl_add_u64 v[18:19], v[18:19], 0, v[148:149]
	v_mul_f32_e32 v196, 0xbfb8aa3b, v16
	v_pk_mul_f32 v[16:17], v[12:13], v[196:197] op_sel_hi:[1,0]
	v_pk_mul_f32 v[20:21], v[14:15], v[196:197] op_sel_hi:[1,0]
	v_pk_mul_f32 v[22:23], v[8:9], v[196:197] op_sel_hi:[1,0]
	v_pk_mul_f32 v[24:25], v[10:11], v[196:197] op_sel_hi:[1,0]
	v_pk_mul_f32 v[4:5], v[4:5], v[12:13]
	v_pk_mul_f32 v[6:7], v[6:7], v[14:15]
	v_pk_mul_f32 v[8:9], v[0:1], v[8:9]
	v_pk_mul_f32 v[10:11], v[2:3], v[10:11]
	v_exp_f32_e32 v16, v16
	v_exp_f32_e32 v17, v17
	v_exp_f32_e32 v20, v20
	v_exp_f32_e32 v21, v21
	v_exp_f32_e32 v22, v22
	v_exp_f32_e32 v23, v23
	v_exp_f32_e32 v24, v24
	v_exp_f32_e32 v25, v25
	v_pk_fma_f32 v[16:17], v[16:17], v[196:197], v[196:197] op_sel:[0,1,1] op_sel_hi:[1,1,1]
	v_pk_fma_f32 v[20:21], v[20:21], v[196:197], v[196:197] op_sel:[0,1,1] op_sel_hi:[1,1,1]
	v_pk_fma_f32 v[22:23], v[22:23], v[196:197], v[196:197] op_sel:[0,1,1] op_sel_hi:[1,1,1]
	v_pk_fma_f32 v[24:25], v[24:25], v[196:197], v[196:197] op_sel:[0,1,1] op_sel_hi:[1,1,1]
	v_rcp_f32_e32 v16, v16
	v_rcp_f32_e32 v17, v17
	v_rcp_f32_e32 v20, v20
	v_rcp_f32_e32 v21, v21
	v_rcp_f32_e32 v22, v22
	v_rcp_f32_e32 v23, v23
	v_rcp_f32_e32 v24, v24
	v_rcp_f32_e32 v25, v25
	v_pk_mul_f32 v[4:5], v[4:5], v[16:17]
	v_pk_mul_f32 v[6:7], v[6:7], v[20:21]
	v_pk_mul_f32 v[8:9], v[8:9], v[22:23]
	v_pk_mul_f32 v[10:11], v[10:11], v[24:25]
	v_cvt_pk_bf16_f32 v0, v4, v5
	v_cvt_pk_bf16_f32 v1, v6, v7
	v_cvt_pk_bf16_f32 v2, v8, v9
	v_cvt_pk_bf16_f32 v3, v10, v11
	global_store_dwordx4 v[18:19], v[0:3], off
	s_cbranch_vccnz .LBB0_187
	s_andn2_b64 vcc, exec, s[8:9]
	s_cbranch_vccnz .LBB0_186
	s_barrier
	s_branch .LBB0_186

; __device__ __forceinline__ unsigned cvtpk(float lo, float hi) { f32x2v_ v = {lo, hi}; bf16x2v_ b = __builtin_convertvector(v, bf16x2v_); return __builtin_bit_cast(unsigned, b); }
; __device__ __forceinline__ float row_rs(const float* ssp, int row) { const unsigned long long v = ((const unsigned long long*)ssp)[row];
;     return __builtin_amdgcn_rsqf((float)v * (1.0f / 4294967296.0f) * (1.0f / 1024.0f) + RMS_EPS); }
;     __device__ __forceinline__ void operator()(const f32x4 (&acc)[2][2][4][2], const Unit& u, int wr, int wc, int fr, int fq) const {
;     ...
;             for (int m = 0; m < 4; ++m) { const int row = row0 + ai * HALF + m * 16; const float rs = row_rs(ss, row);
;                 float hv[8];
; #pragma unroll
;                 for (int n = 0; n < 2; ++n)
; #pragma unroll
;                     for (int i = 0; i < 4; ++i) { const float g = acc[ai][0][m][n][i] * rs, uu = acc[ai][1][m][n][i] * rs;
;                         hv[n * 4 + i] = g * __builtin_amdgcn_rcpf(1.0f + __expf(-g)) * uu; }
;                 u32x4 w; w.x = cvtpk(hv[0], hv[1]); w.y = cvtpk(hv[2], hv[3]); w.z = cvtpk(hv[4], hv[5]); w.w = cvtpk(hv[6], hv[7]);
;                 *(u32x4*)(H + (size_t)row * ldh + col0) = w; }
.LBB0_960:
	v_lshl_or_b32 v160, s74, 7, v154
	v_ashrrev_i32_e32 v161, 31, v160
	v_or_b32_e32 v164, 16, v144
	v_ashrrev_i32_e32 v165, 31, v164
	v_lshl_add_u64 v[166:167], v[164:165], 3, s[0:1]
	v_mov_b64_e32 v[146:147], s[20:21]
	v_mad_i64_i32 v[162:163], s[54:55], v144, s67, v[146:147]
	s_andn2_b64 vcc, exec, s[10:11]
	s_mov_b64 s[10:11], -1
	s_waitcnt vmcnt(7)
	v_cvt_f32_u32_e32 v159, v183
	v_cvt_f32_u32_e32 v145, v182
	v_lshlrev_b64 v[148:149], 1, v[160:161]
	v_lshl_add_u64 v[162:163], v[162:163], 0, v[148:149]
	v_fmamk_f32 v145, v145, 0x2f800000, v159
	v_fmamk_f32 v183, v145, 0x3a800000, v158
	v_rsq_f32_e32 v160, v183
	s_nop 0
	v_mul_f32_e32 v182, 0xbfb8aa3b, v160
	v_pk_mul_f32 v[160:161], v[124:125], v[182:183] op_sel_hi:[1,0]
	v_pk_mul_f32 v[168:169], v[126:127], v[182:183] op_sel_hi:[1,0]
	v_pk_mul_f32 v[170:171], v[120:121], v[182:183] op_sel_hi:[1,0]
	v_pk_mul_f32 v[172:173], v[122:123], v[182:183] op_sel_hi:[1,0]
	v_pk_mul_f32 v[116:117], v[116:117], v[124:125]
	v_pk_mul_f32 v[118:119], v[118:119], v[126:127]
	v_pk_mul_f32 v[120:121], v[112:113], v[120:121]
	v_pk_mul_f32 v[122:123], v[114:115], v[122:123]
	v_exp_f32_e32 v160, v160
	v_exp_f32_e32 v161, v161
	v_exp_f32_e32 v168, v168
	v_exp_f32_e32 v169, v169
	v_exp_f32_e32 v170, v170
	v_exp_f32_e32 v171, v171
	v_exp_f32_e32 v172, v172
	v_exp_f32_e32 v173, v173
	v_pk_fma_f32 v[160:161], v[160:161], v[182:183], v[182:183] op_sel:[0,1,1] op_sel_hi:[1,1,1]
	v_pk_fma_f32 v[168:169], v[168:169], v[182:183], v[182:183] op_sel:[0,1,1] op_sel_hi:[1,1,1]
	v_pk_fma_f32 v[170:171], v[170:171], v[182:183], v[182:183] op_sel:[0,1,1] op_sel_hi:[1,1,1]
	v_pk_fma_f32 v[172:173], v[172:173], v[182:183], v[182:183] op_sel:[0,1,1] op_sel_hi:[1,1,1]
	v_rcp_f32_e32 v160, v160
	v_rcp_f32_e32 v161, v161
	v_rcp_f32_e32 v168, v168
	v_rcp_f32_e32 v169, v169
	v_rcp_f32_e32 v170, v170
	v_rcp_f32_e32 v171, v171
	v_rcp_f32_e32 v172, v172
	v_rcp_f32_e32 v173, v173
	v_pk_mul_f32 v[116:117], v[116:117], v[160:161]
	v_pk_mul_f32 v[118:119], v[118:119], v[168:169]
	v_pk_mul_f32 v[120:121], v[120:121], v[170:171]
	v_pk_mul_f32 v[122:123], v[122:123], v[172:173]
	v_cvt_pk_bf16_f32 v112, v116, v117
	v_cvt_pk_bf16_f32 v113, v118, v119
	v_cvt_pk_bf16_f32 v114, v120, v121
	v_cvt_pk_bf16_f32 v115, v122, v123
	global_store_dwordx4 v[162:163], v[112:115], off
	s_nop 0
	s_nop 0
	v_or_b32_e32 v114, 32, v144
	s_waitcnt vmcnt(7)
	v_cvt_f32_u32_e32 v116, v185
	v_cvt_f32_u32_e32 v115, v184
	v_mad_i64_i32 v[112:113], s[54:55], v164, s67, v[146:147]
	v_fmamk_f32 v115, v115, 0x2f800000, v116
	v_fmamk_f32 v185, v115, 0x3a800000, v158
	v_rsq_f32_e32 v116, v185
	v_ashrrev_i32_e32 v115, 31, v114
	v_lshl_add_u64 v[118:119], v[114:115], 3, s[0:1]
	v_lshl_add_u64 v[112:113], v[112:113], 0, v[148:149]
	v_mul_f32_e32 v184, 0xbfb8aa3b, v116
	v_pk_mul_f32 v[116:117], v[108:109], v[184:185] op_sel_hi:[1,0]
	v_pk_mul_f32 v[120:121], v[110:111], v[184:185] op_sel_hi:[1,0]
	v_pk_mul_f32 v[122:123], v[104:105], v[184:185] op_sel_hi:[1,0]
	v_pk_mul_f32 v[124:125], v[106:107], v[184:185] op_sel_hi:[1,0]
	v_pk_mul_f32 v[100:101], v[100:101], v[108:109]
	v_pk_mul_f32 v[102:103], v[102:103], v[110:111]
	v_pk_mul_f32 v[104:105], v[96:97], v[104:105]
	v_pk_mul_f32 v[106:107], v[98:99], v[106:107]
	v_exp_f32_e32 v116, v116
	v_exp_f32_e32 v117, v117
	v_exp_f32_e32 v120, v120
	v_exp_f32_e32 v121, v121
	v_exp_f32_e32 v122, v122
	v_exp_f32_e32 v123, v123
	v_exp_f32_e32 v124, v124
	v_exp_f32_e32 v125, v125
	v_pk_fma_f32 v[116:117], v[116:117], v[184:185], v[184:185] op_sel:[0,1,1] op_sel_hi:[1,1,1]
	v_pk_fma_f32 v[120:121], v[120:121], v[184:185], v[184:185] op_sel:[0,1,1] op_sel_hi:[1,1,1]
	v_pk_fma_f32 v[122:123], v[122:123], v[184:185], v[184:185] op_sel:[0,1,1] op_sel_hi:[1,1,1]
	v_pk_fma_f32 v[124:125], v[124:125], v[184:185], v[184:185] op_sel:[0,1,1] op_sel_hi:[1,1,1]
	v_rcp_f32_e32 v116, v116
	v_rcp_f32_e32 v117, v117
	v_rcp_f32_e32 v120, v120
	v_rcp_f32_e32 v121, v121
	v_rcp_f32_e32 v122, v122
	v_rcp_f32_e32 v123, v123
	v_rcp_f32_e32 v124, v124
	v_rcp_f32_e32 v125, v125
	v_pk_mul_f32 v[100:101], v[100:101], v[116:117]
	v_pk_mul_f32 v[102:103], v[102:103], v[120:121]
	v_pk_mul_f32 v[104:105], v[104:105], v[122:123]
	v_pk_mul_f32 v[106:107], v[106:107], v[124:125]
	v_cvt_pk_bf16_f32 v96, v100, v101
	v_cvt_pk_bf16_f32 v97, v102, v103
	v_cvt_pk_bf16_f32 v98, v104, v105
	v_cvt_pk_bf16_f32 v99, v106, v107
	global_store_dwordx4 v[112:113], v[96:99], off
	s_nop 0
	s_nop 0
	v_or_b32_e32 v98, 48, v144
	s_waitcnt vmcnt(7)
	v_cvt_f32_u32_e32 v100, v187
	v_cvt_f32_u32_e32 v99, v186
	v_mad_i64_i32 v[96:97], s[54:55], v114, s67, v[146:147]
	v_fmamk_f32 v99, v99, 0x2f800000, v100
	v_fmamk_f32 v187, v99, 0x3a800000, v158
	v_rsq_f32_e32 v100, v187
	v_ashrrev_i32_e32 v99, 31, v98
	v_lshl_add_u64 v[102:103], v[98:99], 3, s[0:1]
	v_lshl_add_u64 v[96:97], v[96:97], 0, v[148:149]
	v_mul_f32_e32 v186, 0xbfb8aa3b, v100
	v_pk_mul_f32 v[100:101], v[92:93], v[186:187] op_sel_hi:[1,0]
	v_pk_mul_f32 v[104:105], v[94:95], v[186:187] op_sel_hi:[1,0]
	v_pk_mul_f32 v[106:107], v[88:89], v[186:187] op_sel_hi:[1,0]
	v_pk_mul_f32 v[108:109], v[90:91], v[186:187] op_sel_hi:[1,0]
	v_pk_mul_f32 v[84:85], v[84:85], v[92:93]
	v_pk_mul_f32 v[86:87], v[86:87], v[94:95]
	v_pk_mul_f32 v[88:89], v[80:81], v[88:89]
	v_pk_mul_f32 v[90:91], v[82:83], v[90:91]
	v_exp_f32_e32 v100, v100
	v_exp_f32_e32 v101, v101
	v_exp_f32_e32 v104, v104
	v_exp_f32_e32 v105, v105
	v_exp_f32_e32 v106, v106
	v_exp_f32_e32 v107, v107
	v_exp_f32_e32 v108, v108
	v_exp_f32_e32 v109, v109
	v_pk_fma_f32 v[100:101], v[100:101], v[186:187], v[186:187] op_sel:[0,1,1] op_sel_hi:[1,1,1]
	v_pk_fma_f32 v[104:105], v[104:105], v[186:187], v[186:187] op_sel:[0,1,1] op_sel_hi:[1,1,1]
	v_pk_fma_f32 v[106:107], v[106:107], v[186:187], v[186:187] op_sel:[0,1,1] op_sel_hi:[1,1,1]
	v_pk_fma_f32 v[108:109], v[108:109], v[186:187], v[186:187] op_sel:[0,1,1] op_sel_hi:[1,1,1]
	v_rcp_f32_e32 v100, v100
	v_rcp_f32_e32 v101, v101
	v_rcp_f32_e32 v104, v104
	v_rcp_f32_e32 v105, v105
	v_rcp_f32_e32 v106, v106
	v_rcp_f32_e32 v107, v107
	v_rcp_f32_e32 v108, v108
	v_rcp_f32_e32 v109, v109
	v_pk_mul_f32 v[84:85], v[84:85], v[100:101]
	v_pk_mul_f32 v[86:87], v[86:87], v[104:105]
	v_pk_mul_f32 v[88:89], v[88:89], v[106:107]
	v_pk_mul_f32 v[90:91], v[90:91], v[108:109]
	v_cvt_pk_bf16_f32 v80, v84, v85
	v_cvt_pk_bf16_f32 v81, v86, v87
	v_cvt_pk_bf16_f32 v82, v88, v89
	v_cvt_pk_bf16_f32 v83, v90, v91
	global_store_dwordx4 v[96:97], v[80:83], off
	s_nop 0
	s_waitcnt vmcnt(7)
; __device__ __forceinline__ unsigned cvtpk(float lo, float hi) { f32x2v_ v = {lo, hi}; bf16x2v_ b = __builtin_convertvector(v, bf16x2v_); return __builtin_bit_cast(unsigned, b); }
; __device__ __forceinline__ float row_rs(const float* ssp, int row) { const unsigned long long v = ((const unsigned long long*)ssp)[row];
;     return __builtin_amdgcn_rsqf((float)v * (1.0f / 4294967296.0f) * (1.0f / 1024.0f) + RMS_EPS); }
;     __device__ __forceinline__ void operator()(const f32x4 (&acc)[2][2][4][2], const Unit& u, int wr, int wc, int fr, int fq) const {
;     ...
;             for (int m = 0; m < 4; ++m) { const int row = row0 + ai * HALF + m * 16; const float rs = row_rs(ss, row);
;                 float hv[8];
; #pragma unroll
;                 for (int n = 0; n < 2; ++n)
; #pragma unroll
;                     for (int i = 0; i < 4; ++i) { const float g = acc[ai][0][m][n][i] * rs, uu = acc[ai][1][m][n][i] * rs;
;                         hv[n * 4 + i] = g * __builtin_amdgcn_rcpf(1.0f + __expf(-g)) * uu; }
;                 u32x4 w; w.x = cvtpk(hv[0], hv[1]); w.y = cvtpk(hv[2], hv[3]); w.z = cvtpk(hv[4], hv[5]); w.w = cvtpk(hv[6], hv[7]);
;                 *(u32x4*)(H + (size_t)row * ldh + col0) = w; }
	v_cvt_f32_u32_e32 v80, v189
	v_cvt_f32_u32_e32 v81, v188
	v_mad_i64_i32 v[82:83], s[54:55], v98, s67, v[146:147]
	v_fmamk_f32 v80, v81, 0x2f800000, v80
	v_fmamk_f32 v189, v80, 0x3a800000, v158
	v_rsq_f32_e32 v80, v189
	v_lshl_add_u64 v[82:83], v[82:83], 0, v[148:149]
	v_mul_f32_e32 v188, 0xbfb8aa3b, v80
	v_pk_mul_f32 v[80:81], v[76:77], v[188:189] op_sel_hi:[1,0]
	v_pk_mul_f32 v[84:85], v[78:79], v[188:189] op_sel_hi:[1,0]
	v_pk_mul_f32 v[86:87], v[72:73], v[188:189] op_sel_hi:[1,0]
	v_pk_mul_f32 v[88:89], v[74:75], v[188:189] op_sel_hi:[1,0]
	v_pk_mul_f32 v[68:69], v[68:69], v[76:77]
	v_pk_mul_f32 v[70:71], v[70:71], v[78:79]
	v_pk_mul_f32 v[72:73], v[64:65], v[72:73]
	v_pk_mul_f32 v[74:75], v[66:67], v[74:75]
	v_exp_f32_e32 v80, v80
	v_exp_f32_e32 v81, v81
	v_exp_f32_e32 v84, v84
	v_exp_f32_e32 v85, v85
	v_exp_f32_e32 v86, v86
	v_exp_f32_e32 v87, v87
	v_exp_f32_e32 v88, v88
	v_exp_f32_e32 v89, v89
	v_pk_fma_f32 v[80:81], v[80:81], v[188:189], v[188:189] op_sel:[0,1,1] op_sel_hi:[1,1,1]
	v_pk_fma_f32 v[84:85], v[84:85], v[188:189], v[188:189] op_sel:[0,1,1] op_sel_hi:[1,1,1]
	v_pk_fma_f32 v[86:87], v[86:87], v[188:189], v[188:189] op_sel:[0,1,1] op_sel_hi:[1,1,1]
	v_pk_fma_f32 v[88:89], v[88:89], v[188:189], v[188:189] op_sel:[0,1,1] op_sel_hi:[1,1,1]
	v_rcp_f32_e32 v80, v80
	v_rcp_f32_e32 v81, v81
	v_rcp_f32_e32 v84, v84
	v_rcp_f32_e32 v85, v85
	v_rcp_f32_e32 v86, v86
	v_rcp_f32_e32 v87, v87
	v_rcp_f32_e32 v88, v88
	v_rcp_f32_e32 v89, v89
	v_pk_mul_f32 v[68:69], v[68:69], v[80:81]
	v_pk_mul_f32 v[70:71], v[70:71], v[84:85]
	v_pk_mul_f32 v[72:73], v[72:73], v[86:87]
	v_pk_mul_f32 v[74:75], v[74:75], v[88:89]
	v_cvt_pk_bf16_f32 v64, v68, v69
	v_cvt_pk_bf16_f32 v65, v70, v71
	v_cvt_pk_bf16_f32 v66, v72, v73
	v_cvt_pk_bf16_f32 v67, v74, v75
	global_store_dwordx4 v[82:83], v[64:67], off
	s_nop 0
	s_waitcnt vmcnt(7)
	v_cvt_f32_u32_e32 v64, v191
	v_cvt_f32_u32_e32 v66, v190
	v_add_u32_e32 v65, 0x80, v144
	v_fmamk_f32 v64, v66, 0x2f800000, v64
	v_fmamk_f32 v191, v64, 0x3a800000, v158
	v_rsq_f32_e32 v64, v191
	v_mad_i64_i32 v[66:67], s[54:55], v65, s67, v[146:147]
	v_lshl_add_u64 v[66:67], v[66:67], 0, v[148:149]
	v_mul_f32_e32 v190, 0xbfb8aa3b, v64
	v_pk_mul_f32 v[64:65], v[60:61], v[190:191] op_sel_hi:[1,0]
	v_pk_mul_f32 v[68:69], v[62:63], v[190:191] op_sel_hi:[1,0]
	v_pk_mul_f32 v[70:71], v[56:57], v[190:191] op_sel_hi:[1,0]
	v_pk_mul_f32 v[72:73], v[58:59], v[190:191] op_sel_hi:[1,0]
	v_pk_mul_f32 v[52:53], v[52:53], v[60:61]
	v_pk_mul_f32 v[54:55], v[54:55], v[62:63]
	v_pk_mul_f32 v[56:57], v[48:49], v[56:57]
	v_pk_mul_f32 v[58:59], v[50:51], v[58:59]
	v_exp_f32_e32 v64, v64
	v_exp_f32_e32 v65, v65
	v_exp_f32_e32 v68, v68
	v_exp_f32_e32 v69, v69
	v_exp_f32_e32 v70, v70
	v_exp_f32_e32 v71, v71
	v_exp_f32_e32 v72, v72
	v_exp_f32_e32 v73, v73
	v_pk_fma_f32 v[64:65], v[64:65], v[190:191], v[190:191] op_sel:[0,1,1] op_sel_hi:[1,1,1]
	v_pk_fma_f32 v[68:69], v[68:69], v[190:191], v[190:191] op_sel:[0,1,1] op_sel_hi:[1,1,1]
	v_pk_fma_f32 v[70:71], v[70:71], v[190:191], v[190:191] op_sel:[0,1,1] op_sel_hi:[1,1,1]
	v_pk_fma_f32 v[72:73], v[72:73], v[190:191], v[190:191] op_sel:[0,1,1] op_sel_hi:[1,1,1]
	v_rcp_f32_e32 v64, v64
	v_rcp_f32_e32 v65, v65
	v_rcp_f32_e32 v68, v68
	v_rcp_f32_e32 v69, v69
	v_rcp_f32_e32 v70, v70
	v_rcp_f32_e32 v71, v71
	v_rcp_f32_e32 v72, v72
	v_rcp_f32_e32 v73, v73
	v_pk_mul_f32 v[52:53], v[52:53], v[64:65]
	v_pk_mul_f32 v[54:55], v[54:55], v[68:69]
	v_pk_mul_f32 v[56:57], v[56:57], v[70:71]
	v_pk_mul_f32 v[58:59], v[58:59], v[72:73]
	v_cvt_pk_bf16_f32 v48, v52, v53
	v_cvt_pk_bf16_f32 v49, v54, v55
	v_cvt_pk_bf16_f32 v50, v56, v57
	v_cvt_pk_bf16_f32 v51, v58, v59
	global_store_dwordx4 v[66:67], v[48:51], off
	s_nop 0
	s_waitcnt vmcnt(7)
	v_cvt_f32_u32_e32 v48, v193
	v_cvt_f32_u32_e32 v50, v192
	v_add_u32_e32 v49, 0x90, v144
	v_fmamk_f32 v48, v50, 0x2f800000, v48
	v_fmamk_f32 v193, v48, 0x3a800000, v158
	v_rsq_f32_e32 v48, v193
	v_mad_i64_i32 v[50:51], s[54:55], v49, s67, v[146:147]
	v_lshl_add_u64 v[50:51], v[50:51], 0, v[148:149]
	v_mul_f32_e32 v192, 0xbfb8aa3b, v48
	v_pk_mul_f32 v[48:49], v[44:45], v[192:193] op_sel_hi:[1,0]
	v_pk_mul_f32 v[52:53], v[46:47], v[192:193] op_sel_hi:[1,0]
	v_pk_mul_f32 v[54:55], v[40:41], v[192:193] op_sel_hi:[1,0]
	v_pk_mul_f32 v[56:57], v[42:43], v[192:193] op_sel_hi:[1,0]
	v_pk_mul_f32 v[36:37], v[36:37], v[44:45]
	v_pk_mul_f32 v[38:39], v[38:39], v[46:47]
	v_pk_mul_f32 v[40:41], v[32:33], v[40:41]
	v_pk_mul_f32 v[42:43], v[34:35], v[42:43]
	v_exp_f32_e32 v48, v48
	v_exp_f32_e32 v49, v49
	v_exp_f32_e32 v52, v52
	v_exp_f32_e32 v53, v53
	v_exp_f32_e32 v54, v54
	v_exp_f32_e32 v55, v55
	v_exp_f32_e32 v56, v56
	v_exp_f32_e32 v57, v57
	v_pk_fma_f32 v[48:49], v[48:49], v[192:193], v[192:193] op_sel:[0,1,1] op_sel_hi:[1,1,1]
	v_pk_fma_f32 v[52:53], v[52:53], v[192:193], v[192:193] op_sel:[0,1,1] op_sel_hi:[1,1,1]
	v_pk_fma_f32 v[54:55], v[54:55], v[192:193], v[192:193] op_sel:[0,1,1] op_sel_hi:[1,1,1]
	v_pk_fma_f32 v[56:57], v[56:57], v[192:193], v[192:193] op_sel:[0,1,1] op_sel_hi:[1,1,1]
	v_rcp_f32_e32 v48, v48
	v_rcp_f32_e32 v49, v49
	v_rcp_f32_e32 v52, v52
	v_rcp_f32_e32 v53, v53
	v_rcp_f32_e32 v54, v54
	v_rcp_f32_e32 v55, v55
	v_rcp_f32_e32 v56, v56
	v_rcp_f32_e32 v57, v57
	v_pk_mul_f32 v[36:37], v[36:37], v[48:49]
	v_pk_mul_f32 v[38:39], v[38:39], v[52:53]
	v_pk_mul_f32 v[40:41], v[40:41], v[54:55]
	v_pk_mul_f32 v[42:43], v[42:43], v[56:57]
	v_cvt_pk_bf16_f32 v32, v36, v37
	v_cvt_pk_bf16_f32 v33, v38, v39
	v_cvt_pk_bf16_f32 v34, v40, v41
	v_cvt_pk_bf16_f32 v35, v42, v43
	global_store_dwordx4 v[50:51], v[32:35], off
	s_nop 0
	s_waitcnt vmcnt(7)
; __device__ __forceinline__ unsigned cvtpk(float lo, float hi) { f32x2v_ v = {lo, hi}; bf16x2v_ b = __builtin_convertvector(v, bf16x2v_); return __builtin_bit_cast(unsigned, b); }
; __device__ __forceinline__ float row_rs(const float* ssp, int row) { const unsigned long long v = ((const unsigned long long*)ssp)[row];
;     return __builtin_amdgcn_rsqf((float)v * (1.0f / 4294967296.0f) * (1.0f / 1024.0f) + RMS_EPS); }
;     __device__ __forceinline__ void operator()(const f32x4 (&acc)[2][2][4][2], const Unit& u, int wr, int wc, int fr, int fq) const {
;     ...
;             for (int m = 0; m < 4; ++m) { const int row = row0 + ai * HALF + m * 16; const float rs = row_rs(ss, row);
;                 float hv[8];
; #pragma unroll
;                 for (int n = 0; n < 2; ++n)
; #pragma unroll
;                     for (int i = 0; i < 4; ++i) { const float g = acc[ai][0][m][n][i] * rs, uu = acc[ai][1][m][n][i] * rs;
;                         hv[n * 4 + i] = g * __builtin_amdgcn_rcpf(1.0f + __expf(-g)) * uu; }
;                 u32x4 w; w.x = cvtpk(hv[0], hv[1]); w.y = cvtpk(hv[2], hv[3]); w.z = cvtpk(hv[4], hv[5]); w.w = cvtpk(hv[6], hv[7]);
;                 *(u32x4*)(H + (size_t)row * ldh + col0) = w; }
	v_cvt_f32_u32_e32 v32, v195
	v_cvt_f32_u32_e32 v34, v194
	v_add_u32_e32 v33, 0xa0, v144
	v_fmamk_f32 v32, v34, 0x2f800000, v32
	v_fmamk_f32 v195, v32, 0x3a800000, v158
	v_rsq_f32_e32 v32, v195
	v_mad_i64_i32 v[34:35], s[54:55], v33, s67, v[146:147]
	v_lshl_add_u64 v[34:35], v[34:35], 0, v[148:149]
	v_mul_f32_e32 v194, 0xbfb8aa3b, v32
	v_pk_mul_f32 v[32:33], v[28:29], v[194:195] op_sel_hi:[1,0]
	v_pk_mul_f32 v[36:37], v[30:31], v[194:195] op_sel_hi:[1,0]
	v_pk_mul_f32 v[38:39], v[24:25], v[194:195] op_sel_hi:[1,0]
	v_pk_mul_f32 v[40:41], v[26:27], v[194:195] op_sel_hi:[1,0]
	v_pk_mul_f32 v[20:21], v[20:21], v[28:29]
	v_pk_mul_f32 v[22:23], v[22:23], v[30:31]
	v_pk_mul_f32 v[24:25], v[16:17], v[24:25]
	v_pk_mul_f32 v[26:27], v[18:19], v[26:27]
	v_exp_f32_e32 v32, v32
	v_exp_f32_e32 v33, v33
	v_exp_f32_e32 v36, v36
	v_exp_f32_e32 v37, v37
	v_exp_f32_e32 v38, v38
	v_exp_f32_e32 v39, v39
	v_exp_f32_e32 v40, v40
	v_exp_f32_e32 v41, v41
	v_pk_fma_f32 v[32:33], v[32:33], v[194:195], v[194:195] op_sel:[0,1,1] op_sel_hi:[1,1,1]
	v_pk_fma_f32 v[36:37], v[36:37], v[194:195], v[194:195] op_sel:[0,1,1] op_sel_hi:[1,1,1]
	v_pk_fma_f32 v[38:39], v[38:39], v[194:195], v[194:195] op_sel:[0,1,1] op_sel_hi:[1,1,1]
	v_pk_fma_f32 v[40:41], v[40:41], v[194:195], v[194:195] op_sel:[0,1,1] op_sel_hi:[1,1,1]
	v_rcp_f32_e32 v32, v32
	v_rcp_f32_e32 v33, v33
	v_rcp_f32_e32 v36, v36
	v_rcp_f32_e32 v37, v37
	v_rcp_f32_e32 v38, v38
	v_rcp_f32_e32 v39, v39
	v_rcp_f32_e32 v40, v40
	v_rcp_f32_e32 v41, v41
	v_pk_mul_f32 v[20:21], v[20:21], v[32:33]
	v_pk_mul_f32 v[22:23], v[22:23], v[36:37]
	v_pk_mul_f32 v[24:25], v[24:25], v[38:39]
	v_pk_mul_f32 v[26:27], v[26:27], v[40:41]
	v_cvt_pk_bf16_f32 v16, v20, v21
	v_cvt_pk_bf16_f32 v17, v22, v23
	v_cvt_pk_bf16_f32 v18, v24, v25
	v_cvt_pk_bf16_f32 v19, v26, v27
	global_store_dwordx4 v[34:35], v[16:19], off
	s_nop 0
	s_waitcnt vmcnt(7)
	v_cvt_f32_u32_e32 v16, v197
	v_cvt_f32_u32_e32 v18, v196
	v_add_u32_e32 v17, 0xb0, v144
	v_fmamk_f32 v16, v18, 0x2f800000, v16
	v_fmamk_f32 v197, v16, 0x3a800000, v158
	v_rsq_f32_e32 v16, v197
	v_mad_i64_i32 v[18:19], s[54:55], v17, s67, v[146:147]
	v_lshl_add_u64 v[18:19], v[18:19], 0, v[148:149]
	v_mul_f32_e32 v196, 0xbfb8aa3b, v16
	v_pk_mul_f32 v[16:17], v[12:13], v[196:197] op_sel_hi:[1,0]
	v_pk_mul_f32 v[20:21], v[14:15], v[196:197] op_sel_hi:[1,0]
	v_pk_mul_f32 v[22:23], v[8:9], v[196:197] op_sel_hi:[1,0]
	v_pk_mul_f32 v[24:25], v[10:11], v[196:197] op_sel_hi:[1,0]
	v_pk_mul_f32 v[4:5], v[4:5], v[12:13]
	v_pk_mul_f32 v[6:7], v[6:7], v[14:15]
	v_pk_mul_f32 v[8:9], v[0:1], v[8:9]
	v_pk_mul_f32 v[10:11], v[2:3], v[10:11]
	v_exp_f32_e32 v16, v16
	v_exp_f32_e32 v17, v17
	v_exp_f32_e32 v20, v20
	v_exp_f32_e32 v21, v21
	v_exp_f32_e32 v22, v22
	v_exp_f32_e32 v23, v23
	v_exp_f32_e32 v24, v24
	v_exp_f32_e32 v25, v25
	v_pk_fma_f32 v[16:17], v[16:17], v[196:197], v[196:197] op_sel:[0,1,1] op_sel_hi:[1,1,1]
	v_pk_fma_f32 v[20:21], v[20:21], v[196:197], v[196:197] op_sel:[0,1,1] op_sel_hi:[1,1,1]
	v_pk_fma_f32 v[22:23], v[22:23], v[196:197], v[196:197] op_sel:[0,1,1] op_sel_hi:[1,1,1]
	v_pk_fma_f32 v[24:25], v[24:25], v[196:197], v[196:197] op_sel:[0,1,1] op_sel_hi:[1,1,1]
	v_rcp_f32_e32 v16, v16
	v_rcp_f32_e32 v17, v17
	v_rcp_f32_e32 v20, v20
	v_rcp_f32_e32 v21, v21
	v_rcp_f32_e32 v22, v22
	v_rcp_f32_e32 v23, v23
	v_rcp_f32_e32 v24, v24
	v_rcp_f32_e32 v25, v25
	v_pk_mul_f32 v[4:5], v[4:5], v[16:17]
	v_pk_mul_f32 v[6:7], v[6:7], v[20:21]
	v_pk_mul_f32 v[8:9], v[8:9], v[22:23]
	v_pk_mul_f32 v[10:11], v[10:11], v[24:25]
	v_cvt_pk_bf16_f32 v0, v4, v5
	v_cvt_pk_bf16_f32 v1, v6, v7
	v_cvt_pk_bf16_f32 v2, v8, v9
	v_cvt_pk_bf16_f32 v3, v10, v11
	global_store_dwordx4 v[18:19], v[0:3], off
	s_cbranch_vccnz .LBB0_953
	s_andn2_b64 vcc, exec, s[12:13]
	s_cbranch_vccnz .LBB0_952
	s_barrier
	s_branch .LBB0_952

; __device__ __forceinline__ unsigned cvtpk(float lo, float hi) { f32x2v_ v = {lo, hi}; bf16x2v_ b = __builtin_convertvector(v, bf16x2v_); return __builtin_bit_cast(unsigned, b); }
; __device__ __forceinline__ float row_rs(const float* ssp, int row) { const unsigned long long v = ((const unsigned long long*)ssp)[row];
;     return __builtin_amdgcn_rsqf((float)v * (1.0f / 4294967296.0f) * (1.0f / 1024.0f) + RMS_EPS); }
;     __device__ __forceinline__ void operator()(const f32x4 (&acc)[2][2][4][2], const Unit& u, int wr, int wc, int fr, int fq) const {
;     ...
;             for (int m = 0; m < 4; ++m) { const int row = row0 + ai * HALF + m * 16; const float rs = row_rs(ss, row);
;                 float hv[8];
; #pragma unroll
;                 for (int n = 0; n < 2; ++n)
; #pragma unroll
;                     for (int i = 0; i < 4; ++i) { const float g = acc[ai][0][m][n][i] * rs, uu = acc[ai][1][m][n][i] * rs;
;                         hv[n * 4 + i] = g * __builtin_amdgcn_rcpf(1.0f + __expf(-g)) * uu; }
;                 u32x4 w; w.x = cvtpk(hv[0], hv[1]); w.y = cvtpk(hv[2], hv[3]); w.z = cvtpk(hv[4], hv[5]); w.w = cvtpk(hv[6], hv[7]);
;                 *(u32x4*)(H + (size_t)row * ldh + col0) = w; }
.LBB0_1122:
	v_lshl_or_b32 v160, s75, 7, v154
	v_ashrrev_i32_e32 v161, 31, v160
	v_or_b32_e32 v164, 16, v144
	v_ashrrev_i32_e32 v165, 31, v164
	v_lshl_add_u64 v[166:167], v[164:165], 3, s[36:37]
	v_mov_b64_e32 v[146:147], s[20:21]
	v_mad_i64_i32 v[162:163], s[54:55], v144, s74, v[146:147]
	s_andn2_b64 vcc, exec, s[10:11]
	s_mov_b64 s[10:11], -1
	s_waitcnt vmcnt(7)
	v_cvt_f32_u32_e32 v159, v183
	v_cvt_f32_u32_e32 v145, v182
	v_lshlrev_b64 v[148:149], 1, v[160:161]
	v_lshl_add_u64 v[162:163], v[162:163], 0, v[148:149]
	v_fmamk_f32 v145, v145, 0x2f800000, v159
	v_fmamk_f32 v183, v145, 0x3a800000, v158
	v_rsq_f32_e32 v160, v183
	s_nop 0
	v_mul_f32_e32 v182, 0xbfb8aa3b, v160
	v_pk_mul_f32 v[160:161], v[124:125], v[182:183] op_sel_hi:[1,0]
	v_pk_mul_f32 v[168:169], v[126:127], v[182:183] op_sel_hi:[1,0]
	v_pk_mul_f32 v[170:171], v[120:121], v[182:183] op_sel_hi:[1,0]
	v_pk_mul_f32 v[172:173], v[122:123], v[182:183] op_sel_hi:[1,0]
	v_pk_mul_f32 v[116:117], v[116:117], v[124:125]
	v_pk_mul_f32 v[118:119], v[118:119], v[126:127]
	v_pk_mul_f32 v[120:121], v[112:113], v[120:121]
	v_pk_mul_f32 v[122:123], v[114:115], v[122:123]
	v_exp_f32_e32 v160, v160
	v_exp_f32_e32 v161, v161
	v_exp_f32_e32 v168, v168
	v_exp_f32_e32 v169, v169
	v_exp_f32_e32 v170, v170
	v_exp_f32_e32 v171, v171
	v_exp_f32_e32 v172, v172
	v_exp_f32_e32 v173, v173
	v_pk_fma_f32 v[160:161], v[160:161], v[182:183], v[182:183] op_sel:[0,1,1] op_sel_hi:[1,1,1]
	v_pk_fma_f32 v[168:169], v[168:169], v[182:183], v[182:183] op_sel:[0,1,1] op_sel_hi:[1,1,1]
	v_pk_fma_f32 v[170:171], v[170:171], v[182:183], v[182:183] op_sel:[0,1,1] op_sel_hi:[1,1,1]
	v_pk_fma_f32 v[172:173], v[172:173], v[182:183], v[182:183] op_sel:[0,1,1] op_sel_hi:[1,1,1]
	v_rcp_f32_e32 v160, v160
	v_rcp_f32_e32 v161, v161
	v_rcp_f32_e32 v168, v168
	v_rcp_f32_e32 v169, v169
	v_rcp_f32_e32 v170, v170
	v_rcp_f32_e32 v171, v171
	v_rcp_f32_e32 v172, v172
	v_rcp_f32_e32 v173, v173
	v_pk_mul_f32 v[116:117], v[116:117], v[160:161]
	v_pk_mul_f32 v[118:119], v[118:119], v[168:169]
	v_pk_mul_f32 v[120:121], v[120:121], v[170:171]
	v_pk_mul_f32 v[122:123], v[122:123], v[172:173]
	v_cvt_pk_bf16_f32 v112, v116, v117
	v_cvt_pk_bf16_f32 v113, v118, v119
	v_cvt_pk_bf16_f32 v114, v120, v121
	v_cvt_pk_bf16_f32 v115, v122, v123
	global_store_dwordx4 v[162:163], v[112:115], off
	s_nop 0
	s_nop 0
	v_or_b32_e32 v114, 32, v144
	s_waitcnt vmcnt(7)
	v_cvt_f32_u32_e32 v116, v185
	v_cvt_f32_u32_e32 v115, v184
	v_mad_i64_i32 v[112:113], s[54:55], v164, s74, v[146:147]
	v_fmamk_f32 v115, v115, 0x2f800000, v116
	v_fmamk_f32 v185, v115, 0x3a800000, v158
	v_rsq_f32_e32 v116, v185
	v_ashrrev_i32_e32 v115, 31, v114
	v_lshl_add_u64 v[118:119], v[114:115], 3, s[36:37]
	v_lshl_add_u64 v[112:113], v[112:113], 0, v[148:149]
	v_mul_f32_e32 v184, 0xbfb8aa3b, v116
	v_pk_mul_f32 v[116:117], v[108:109], v[184:185] op_sel_hi:[1,0]
	v_pk_mul_f32 v[120:121], v[110:111], v[184:185] op_sel_hi:[1,0]
	v_pk_mul_f32 v[122:123], v[104:105], v[184:185] op_sel_hi:[1,0]
	v_pk_mul_f32 v[124:125], v[106:107], v[184:185] op_sel_hi:[1,0]
	v_pk_mul_f32 v[100:101], v[100:101], v[108:109]
	v_pk_mul_f32 v[102:103], v[102:103], v[110:111]
	v_pk_mul_f32 v[104:105], v[96:97], v[104:105]
	v_pk_mul_f32 v[106:107], v[98:99], v[106:107]
	v_exp_f32_e32 v116, v116
	v_exp_f32_e32 v117, v117
	v_exp_f32_e32 v120, v120
	v_exp_f32_e32 v121, v121
	v_exp_f32_e32 v122, v122
	v_exp_f32_e32 v123, v123
	v_exp_f32_e32 v124, v124
	v_exp_f32_e32 v125, v125
	v_pk_fma_f32 v[116:117], v[116:117], v[184:185], v[184:185] op_sel:[0,1,1] op_sel_hi:[1,1,1]
	v_pk_fma_f32 v[120:121], v[120:121], v[184:185], v[184:185] op_sel:[0,1,1] op_sel_hi:[1,1,1]
	v_pk_fma_f32 v[122:123], v[122:123], v[184:185], v[184:185] op_sel:[0,1,1] op_sel_hi:[1,1,1]
	v_pk_fma_f32 v[124:125], v[124:125], v[184:185], v[184:185] op_sel:[0,1,1] op_sel_hi:[1,1,1]
	v_rcp_f32_e32 v116, v116
	v_rcp_f32_e32 v117, v117
	v_rcp_f32_e32 v120, v120
	v_rcp_f32_e32 v121, v121
	v_rcp_f32_e32 v122, v122
	v_rcp_f32_e32 v123, v123
	v_rcp_f32_e32 v124, v124
	v_rcp_f32_e32 v125, v125
	v_pk_mul_f32 v[100:101], v[100:101], v[116:117]
	v_pk_mul_f32 v[102:103], v[102:103], v[120:121]
	v_pk_mul_f32 v[104:105], v[104:105], v[122:123]
	v_pk_mul_f32 v[106:107], v[106:107], v[124:125]
	v_cvt_pk_bf16_f32 v96, v100, v101
	v_cvt_pk_bf16_f32 v97, v102, v103
	v_cvt_pk_bf16_f32 v98, v104, v105
	v_cvt_pk_bf16_f32 v99, v106, v107
	global_store_dwordx4 v[112:113], v[96:99], off
	s_nop 0
	s_nop 0
	v_or_b32_e32 v98, 48, v144
	s_waitcnt vmcnt(7)
	v_cvt_f32_u32_e32 v100, v187
	v_cvt_f32_u32_e32 v99, v186
	v_mad_i64_i32 v[96:97], s[54:55], v114, s74, v[146:147]
	v_fmamk_f32 v99, v99, 0x2f800000, v100
	v_fmamk_f32 v187, v99, 0x3a800000, v158
	v_rsq_f32_e32 v100, v187
	v_ashrrev_i32_e32 v99, 31, v98
	v_lshl_add_u64 v[102:103], v[98:99], 3, s[36:37]
	v_lshl_add_u64 v[96:97], v[96:97], 0, v[148:149]
	v_mul_f32_e32 v186, 0xbfb8aa3b, v100
	v_pk_mul_f32 v[100:101], v[92:93], v[186:187] op_sel_hi:[1,0]
	v_pk_mul_f32 v[104:105], v[94:95], v[186:187] op_sel_hi:[1,0]
	v_pk_mul_f32 v[106:107], v[88:89], v[186:187] op_sel_hi:[1,0]
	v_pk_mul_f32 v[108:109], v[90:91], v[186:187] op_sel_hi:[1,0]
	v_pk_mul_f32 v[84:85], v[84:85], v[92:93]
	v_pk_mul_f32 v[86:87], v[86:87], v[94:95]
	v_pk_mul_f32 v[88:89], v[80:81], v[88:89]
	v_pk_mul_f32 v[90:91], v[82:83], v[90:91]
	v_exp_f32_e32 v100, v100
	v_exp_f32_e32 v101, v101
	v_exp_f32_e32 v104, v104
	v_exp_f32_e32 v105, v105
	v_exp_f32_e32 v106, v106
	v_exp_f32_e32 v107, v107
	v_exp_f32_e32 v108, v108
	v_exp_f32_e32 v109, v109
	v_pk_fma_f32 v[100:101], v[100:101], v[186:187], v[186:187] op_sel:[0,1,1] op_sel_hi:[1,1,1]
	v_pk_fma_f32 v[104:105], v[104:105], v[186:187], v[186:187] op_sel:[0,1,1] op_sel_hi:[1,1,1]
	v_pk_fma_f32 v[106:107], v[106:107], v[186:187], v[186:187] op_sel:[0,1,1] op_sel_hi:[1,1,1]
	v_pk_fma_f32 v[108:109], v[108:109], v[186:187], v[186:187] op_sel:[0,1,1] op_sel_hi:[1,1,1]
	v_rcp_f32_e32 v100, v100
	v_rcp_f32_e32 v101, v101
	v_rcp_f32_e32 v104, v104
	v_rcp_f32_e32 v105, v105
	v_rcp_f32_e32 v106, v106
	v_rcp_f32_e32 v107, v107
	v_rcp_f32_e32 v108, v108
	v_rcp_f32_e32 v109, v109
	v_pk_mul_f32 v[84:85], v[84:85], v[100:101]
	v_pk_mul_f32 v[86:87], v[86:87], v[104:105]
	v_pk_mul_f32 v[88:89], v[88:89], v[106:107]
	v_pk_mul_f32 v[90:91], v[90:91], v[108:109]
	v_cvt_pk_bf16_f32 v80, v84, v85
	v_cvt_pk_bf16_f32 v81, v86, v87
	v_cvt_pk_bf16_f32 v82, v88, v89
	v_cvt_pk_bf16_f32 v83, v90, v91
	global_store_dwordx4 v[96:97], v[80:83], off
	s_nop 0
	s_waitcnt vmcnt(7)
; __device__ __forceinline__ unsigned cvtpk(float lo, float hi) { f32x2v_ v = {lo, hi}; bf16x2v_ b = __builtin_convertvector(v, bf16x2v_); return __builtin_bit_cast(unsigned, b); }
; __device__ __forceinline__ float row_rs(const float* ssp, int row) { const unsigned long long v = ((const unsigned long long*)ssp)[row];
;     return __builtin_amdgcn_rsqf((float)v * (1.0f / 4294967296.0f) * (1.0f / 1024.0f) + RMS_EPS); }
;     __device__ __forceinline__ void operator()(const f32x4 (&acc)[2][2][4][2], const Unit& u, int wr, int wc, int fr, int fq) const {
;     ...
;             for (int m = 0; m < 4; ++m) { const int row = row0 + ai * HALF + m * 16; const float rs = row_rs(ss, row);
;                 float hv[8];
; #pragma unroll
;                 for (int n = 0; n < 2; ++n)
; #pragma unroll
;                     for (int i = 0; i < 4; ++i) { const float g = acc[ai][0][m][n][i] * rs, uu = acc[ai][1][m][n][i] * rs;
;                         hv[n * 4 + i] = g * __builtin_amdgcn_rcpf(1.0f + __expf(-g)) * uu; }
;                 u32x4 w; w.x = cvtpk(hv[0], hv[1]); w.y = cvtpk(hv[2], hv[3]); w.z = cvtpk(hv[4], hv[5]); w.w = cvtpk(hv[6], hv[7]);
;                 *(u32x4*)(H + (size_t)row * ldh + col0) = w; }
	v_cvt_f32_u32_e32 v80, v189
	v_cvt_f32_u32_e32 v81, v188
	v_mad_i64_i32 v[82:83], s[54:55], v98, s74, v[146:147]
	v_fmamk_f32 v80, v81, 0x2f800000, v80
	v_fmamk_f32 v189, v80, 0x3a800000, v158
	v_rsq_f32_e32 v80, v189
	v_lshl_add_u64 v[82:83], v[82:83], 0, v[148:149]
	v_mul_f32_e32 v188, 0xbfb8aa3b, v80
	v_pk_mul_f32 v[80:81], v[76:77], v[188:189] op_sel_hi:[1,0]
	v_pk_mul_f32 v[84:85], v[78:79], v[188:189] op_sel_hi:[1,0]
	v_pk_mul_f32 v[86:87], v[72:73], v[188:189] op_sel_hi:[1,0]
	v_pk_mul_f32 v[88:89], v[74:75], v[188:189] op_sel_hi:[1,0]
	v_pk_mul_f32 v[68:69], v[68:69], v[76:77]
	v_pk_mul_f32 v[70:71], v[70:71], v[78:79]
	v_pk_mul_f32 v[72:73], v[64:65], v[72:73]
	v_pk_mul_f32 v[74:75], v[66:67], v[74:75]
	v_exp_f32_e32 v80, v80
	v_exp_f32_e32 v81, v81
	v_exp_f32_e32 v84, v84
	v_exp_f32_e32 v85, v85
	v_exp_f32_e32 v86, v86
	v_exp_f32_e32 v87, v87
	v_exp_f32_e32 v88, v88
	v_exp_f32_e32 v89, v89
	v_pk_fma_f32 v[80:81], v[80:81], v[188:189], v[188:189] op_sel:[0,1,1] op_sel_hi:[1,1,1]
	v_pk_fma_f32 v[84:85], v[84:85], v[188:189], v[188:189] op_sel:[0,1,1] op_sel_hi:[1,1,1]
	v_pk_fma_f32 v[86:87], v[86:87], v[188:189], v[188:189] op_sel:[0,1,1] op_sel_hi:[1,1,1]
	v_pk_fma_f32 v[88:89], v[88:89], v[188:189], v[188:189] op_sel:[0,1,1] op_sel_hi:[1,1,1]
	v_rcp_f32_e32 v80, v80
	v_rcp_f32_e32 v81, v81
	v_rcp_f32_e32 v84, v84
	v_rcp_f32_e32 v85, v85
	v_rcp_f32_e32 v86, v86
	v_rcp_f32_e32 v87, v87
	v_rcp_f32_e32 v88, v88
	v_rcp_f32_e32 v89, v89
	v_pk_mul_f32 v[68:69], v[68:69], v[80:81]
	v_pk_mul_f32 v[70:71], v[70:71], v[84:85]
	v_pk_mul_f32 v[72:73], v[72:73], v[86:87]
	v_pk_mul_f32 v[74:75], v[74:75], v[88:89]
	v_cvt_pk_bf16_f32 v64, v68, v69
	v_cvt_pk_bf16_f32 v65, v70, v71
	v_cvt_pk_bf16_f32 v66, v72, v73
	v_cvt_pk_bf16_f32 v67, v74, v75
	global_store_dwordx4 v[82:83], v[64:67], off
	s_nop 0
	s_waitcnt vmcnt(7)
	v_cvt_f32_u32_e32 v64, v191
	v_cvt_f32_u32_e32 v66, v190
	v_add_u32_e32 v65, 0x80, v144
	v_fmamk_f32 v64, v66, 0x2f800000, v64
	v_fmamk_f32 v191, v64, 0x3a800000, v158
	v_rsq_f32_e32 v64, v191
	v_mad_i64_i32 v[66:67], s[54:55], v65, s74, v[146:147]
	v_lshl_add_u64 v[66:67], v[66:67], 0, v[148:149]
	v_mul_f32_e32 v190, 0xbfb8aa3b, v64
	v_pk_mul_f32 v[64:65], v[60:61], v[190:191] op_sel_hi:[1,0]
	v_pk_mul_f32 v[68:69], v[62:63], v[190:191] op_sel_hi:[1,0]
	v_pk_mul_f32 v[70:71], v[56:57], v[190:191] op_sel_hi:[1,0]
	v_pk_mul_f32 v[72:73], v[58:59], v[190:191] op_sel_hi:[1,0]
	v_pk_mul_f32 v[52:53], v[52:53], v[60:61]
	v_pk_mul_f32 v[54:55], v[54:55], v[62:63]
	v_pk_mul_f32 v[56:57], v[48:49], v[56:57]
	v_pk_mul_f32 v[58:59], v[50:51], v[58:59]
	v_exp_f32_e32 v64, v64
	v_exp_f32_e32 v65, v65
	v_exp_f32_e32 v68, v68
	v_exp_f32_e32 v69, v69
	v_exp_f32_e32 v70, v70
	v_exp_f32_e32 v71, v71
	v_exp_f32_e32 v72, v72
	v_exp_f32_e32 v73, v73
	v_pk_fma_f32 v[64:65], v[64:65], v[190:191], v[190:191] op_sel:[0,1,1] op_sel_hi:[1,1,1]
	v_pk_fma_f32 v[68:69], v[68:69], v[190:191], v[190:191] op_sel:[0,1,1] op_sel_hi:[1,1,1]
	v_pk_fma_f32 v[70:71], v[70:71], v[190:191], v[190:191] op_sel:[0,1,1] op_sel_hi:[1,1,1]
	v_pk_fma_f32 v[72:73], v[72:73], v[190:191], v[190:191] op_sel:[0,1,1] op_sel_hi:[1,1,1]
	v_rcp_f32_e32 v64, v64
	v_rcp_f32_e32 v65, v65
	v_rcp_f32_e32 v68, v68
	v_rcp_f32_e32 v69, v69
	v_rcp_f32_e32 v70, v70
	v_rcp_f32_e32 v71, v71
	v_rcp_f32_e32 v72, v72
	v_rcp_f32_e32 v73, v73
	v_pk_mul_f32 v[52:53], v[52:53], v[64:65]
	v_pk_mul_f32 v[54:55], v[54:55], v[68:69]
	v_pk_mul_f32 v[56:57], v[56:57], v[70:71]
	v_pk_mul_f32 v[58:59], v[58:59], v[72:73]
	v_cvt_pk_bf16_f32 v48, v52, v53
	v_cvt_pk_bf16_f32 v49, v54, v55
	v_cvt_pk_bf16_f32 v50, v56, v57
	v_cvt_pk_bf16_f32 v51, v58, v59
	global_store_dwordx4 v[66:67], v[48:51], off
	s_nop 0
	s_waitcnt vmcnt(7)
	v_cvt_f32_u32_e32 v48, v193
	v_cvt_f32_u32_e32 v50, v192
	v_add_u32_e32 v49, 0x90, v144
	v_fmamk_f32 v48, v50, 0x2f800000, v48
	v_fmamk_f32 v193, v48, 0x3a800000, v158
	v_rsq_f32_e32 v48, v193
	v_mad_i64_i32 v[50:51], s[54:55], v49, s74, v[146:147]
	v_lshl_add_u64 v[50:51], v[50:51], 0, v[148:149]
	v_mul_f32_e32 v192, 0xbfb8aa3b, v48
	v_pk_mul_f32 v[48:49], v[44:45], v[192:193] op_sel_hi:[1,0]
	v_pk_mul_f32 v[52:53], v[46:47], v[192:193] op_sel_hi:[1,0]
	v_pk_mul_f32 v[54:55], v[40:41], v[192:193] op_sel_hi:[1,0]
	v_pk_mul_f32 v[56:57], v[42:43], v[192:193] op_sel_hi:[1,0]
	v_pk_mul_f32 v[36:37], v[36:37], v[44:45]
	v_pk_mul_f32 v[38:39], v[38:39], v[46:47]
	v_pk_mul_f32 v[40:41], v[32:33], v[40:41]
	v_pk_mul_f32 v[42:43], v[34:35], v[42:43]
	v_exp_f32_e32 v48, v48
	v_exp_f32_e32 v49, v49
	v_exp_f32_e32 v52, v52
	v_exp_f32_e32 v53, v53
	v_exp_f32_e32 v54, v54
	v_exp_f32_e32 v55, v55
	v_exp_f32_e32 v56, v56
	v_exp_f32_e32 v57, v57
	v_pk_fma_f32 v[48:49], v[48:49], v[192:193], v[192:193] op_sel:[0,1,1] op_sel_hi:[1,1,1]
	v_pk_fma_f32 v[52:53], v[52:53], v[192:193], v[192:193] op_sel:[0,1,1] op_sel_hi:[1,1,1]
	v_pk_fma_f32 v[54:55], v[54:55], v[192:193], v[192:193] op_sel:[0,1,1] op_sel_hi:[1,1,1]
	v_pk_fma_f32 v[56:57], v[56:57], v[192:193], v[192:193] op_sel:[0,1,1] op_sel_hi:[1,1,1]
	v_rcp_f32_e32 v48, v48
	v_rcp_f32_e32 v49, v49
	v_rcp_f32_e32 v52, v52
	v_rcp_f32_e32 v53, v53
	v_rcp_f32_e32 v54, v54
	v_rcp_f32_e32 v55, v55
	v_rcp_f32_e32 v56, v56
	v_rcp_f32_e32 v57, v57
	v_pk_mul_f32 v[36:37], v[36:37], v[48:49]
	v_pk_mul_f32 v[38:39], v[38:39], v[52:53]
	v_pk_mul_f32 v[40:41], v[40:41], v[54:55]
	v_pk_mul_f32 v[42:43], v[42:43], v[56:57]
	v_cvt_pk_bf16_f32 v32, v36, v37
	v_cvt_pk_bf16_f32 v33, v38, v39
	v_cvt_pk_bf16_f32 v34, v40, v41
	v_cvt_pk_bf16_f32 v35, v42, v43
	global_store_dwordx4 v[50:51], v[32:35], off
	s_nop 0
	s_waitcnt vmcnt(7)
; __device__ __forceinline__ unsigned cvtpk(float lo, float hi) { f32x2v_ v = {lo, hi}; bf16x2v_ b = __builtin_convertvector(v, bf16x2v_); return __builtin_bit_cast(unsigned, b); }
; __device__ __forceinline__ float row_rs(const float* ssp, int row) { const unsigned long long v = ((const unsigned long long*)ssp)[row];
;     return __builtin_amdgcn_rsqf((float)v * (1.0f / 4294967296.0f) * (1.0f / 1024.0f) + RMS_EPS); }
;     __device__ __forceinline__ void operator()(const f32x4 (&acc)[2][2][4][2], const Unit& u, int wr, int wc, int fr, int fq) const {
;     ...
;             for (int m = 0; m < 4; ++m) { const int row = row0 + ai * HALF + m * 16; const float rs = row_rs(ss, row);
;                 float hv[8];
; #pragma unroll
;                 for (int n = 0; n < 2; ++n)
; #pragma unroll
;                     for (int i = 0; i < 4; ++i) { const float g = acc[ai][0][m][n][i] * rs, uu = acc[ai][1][m][n][i] * rs;
;                         hv[n * 4 + i] = g * __builtin_amdgcn_rcpf(1.0f + __expf(-g)) * uu; }
;                 u32x4 w; w.x = cvtpk(hv[0], hv[1]); w.y = cvtpk(hv[2], hv[3]); w.z = cvtpk(hv[4], hv[5]); w.w = cvtpk(hv[6], hv[7]);
;                 *(u32x4*)(H + (size_t)row * ldh + col0) = w; }
	v_cvt_f32_u32_e32 v32, v195
	v_cvt_f32_u32_e32 v34, v194
	v_add_u32_e32 v33, 0xa0, v144
	v_fmamk_f32 v32, v34, 0x2f800000, v32
	v_fmamk_f32 v195, v32, 0x3a800000, v158
	v_rsq_f32_e32 v32, v195
	v_mad_i64_i32 v[34:35], s[54:55], v33, s74, v[146:147]
	v_lshl_add_u64 v[34:35], v[34:35], 0, v[148:149]
	v_mul_f32_e32 v194, 0xbfb8aa3b, v32
	v_pk_mul_f32 v[32:33], v[28:29], v[194:195] op_sel_hi:[1,0]
	v_pk_mul_f32 v[36:37], v[30:31], v[194:195] op_sel_hi:[1,0]
	v_pk_mul_f32 v[38:39], v[24:25], v[194:195] op_sel_hi:[1,0]
	v_pk_mul_f32 v[40:41], v[26:27], v[194:195] op_sel_hi:[1,0]
	v_pk_mul_f32 v[20:21], v[20:21], v[28:29]
	v_pk_mul_f32 v[22:23], v[22:23], v[30:31]
	v_pk_mul_f32 v[24:25], v[16:17], v[24:25]
	v_pk_mul_f32 v[26:27], v[18:19], v[26:27]
	v_exp_f32_e32 v32, v32
	v_exp_f32_e32 v33, v33
	v_exp_f32_e32 v36, v36
	v_exp_f32_e32 v37, v37
	v_exp_f32_e32 v38, v38
	v_exp_f32_e32 v39, v39
	v_exp_f32_e32 v40, v40
	v_exp_f32_e32 v41, v41
	v_pk_fma_f32 v[32:33], v[32:33], v[194:195], v[194:195] op_sel:[0,1,1] op_sel_hi:[1,1,1]
	v_pk_fma_f32 v[36:37], v[36:37], v[194:195], v[194:195] op_sel:[0,1,1] op_sel_hi:[1,1,1]
	v_pk_fma_f32 v[38:39], v[38:39], v[194:195], v[194:195] op_sel:[0,1,1] op_sel_hi:[1,1,1]
	v_pk_fma_f32 v[40:41], v[40:41], v[194:195], v[194:195] op_sel:[0,1,1] op_sel_hi:[1,1,1]
	v_rcp_f32_e32 v32, v32
	v_rcp_f32_e32 v33, v33
	v_rcp_f32_e32 v36, v36
	v_rcp_f32_e32 v37, v37
	v_rcp_f32_e32 v38, v38
	v_rcp_f32_e32 v39, v39
	v_rcp_f32_e32 v40, v40
	v_rcp_f32_e32 v41, v41
	v_pk_mul_f32 v[20:21], v[20:21], v[32:33]
	v_pk_mul_f32 v[22:23], v[22:23], v[36:37]
	v_pk_mul_f32 v[24:25], v[24:25], v[38:39]
	v_pk_mul_f32 v[26:27], v[26:27], v[40:41]
	v_cvt_pk_bf16_f32 v16, v20, v21
	v_cvt_pk_bf16_f32 v17, v22, v23
	v_cvt_pk_bf16_f32 v18, v24, v25
	v_cvt_pk_bf16_f32 v19, v26, v27
	global_store_dwordx4 v[34:35], v[16:19], off
	s_nop 0
	s_waitcnt vmcnt(7)
	v_cvt_f32_u32_e32 v16, v197
	v_cvt_f32_u32_e32 v18, v196
	v_add_u32_e32 v17, 0xb0, v144
	v_fmamk_f32 v16, v18, 0x2f800000, v16
	v_fmamk_f32 v197, v16, 0x3a800000, v158
	v_rsq_f32_e32 v16, v197
	v_mad_i64_i32 v[18:19], s[54:55], v17, s74, v[146:147]
	v_lshl_add_u64 v[18:19], v[18:19], 0, v[148:149]
	v_mul_f32_e32 v196, 0xbfb8aa3b, v16
	v_pk_mul_f32 v[16:17], v[12:13], v[196:197] op_sel_hi:[1,0]
	v_pk_mul_f32 v[20:21], v[14:15], v[196:197] op_sel_hi:[1,0]
	v_pk_mul_f32 v[22:23], v[8:9], v[196:197] op_sel_hi:[1,0]
	v_pk_mul_f32 v[24:25], v[10:11], v[196:197] op_sel_hi:[1,0]
	v_pk_mul_f32 v[4:5], v[4:5], v[12:13]
	v_pk_mul_f32 v[6:7], v[6:7], v[14:15]
	v_pk_mul_f32 v[8:9], v[0:1], v[8:9]
	v_pk_mul_f32 v[10:11], v[2:3], v[10:11]
	v_exp_f32_e32 v16, v16
	v_exp_f32_e32 v17, v17
	v_exp_f32_e32 v20, v20
	v_exp_f32_e32 v21, v21
	v_exp_f32_e32 v22, v22
	v_exp_f32_e32 v23, v23
	v_exp_f32_e32 v24, v24
	v_exp_f32_e32 v25, v25
	v_pk_fma_f32 v[16:17], v[16:17], v[196:197], v[196:197] op_sel:[0,1,1] op_sel_hi:[1,1,1]
	v_pk_fma_f32 v[20:21], v[20:21], v[196:197], v[196:197] op_sel:[0,1,1] op_sel_hi:[1,1,1]
	v_pk_fma_f32 v[22:23], v[22:23], v[196:197], v[196:197] op_sel:[0,1,1] op_sel_hi:[1,1,1]
	v_pk_fma_f32 v[24:25], v[24:25], v[196:197], v[196:197] op_sel:[0,1,1] op_sel_hi:[1,1,1]
	v_rcp_f32_e32 v16, v16
	v_rcp_f32_e32 v17, v17
	v_rcp_f32_e32 v20, v20
	v_rcp_f32_e32 v21, v21
	v_rcp_f32_e32 v22, v22
	v_rcp_f32_e32 v23, v23
	v_rcp_f32_e32 v24, v24
	v_rcp_f32_e32 v25, v25
	v_pk_mul_f32 v[4:5], v[4:5], v[16:17]
	v_pk_mul_f32 v[6:7], v[6:7], v[20:21]
	v_pk_mul_f32 v[8:9], v[8:9], v[22:23]
	v_pk_mul_f32 v[10:11], v[10:11], v[24:25]
	v_cvt_pk_bf16_f32 v0, v4, v5
	v_cvt_pk_bf16_f32 v1, v6, v7
	v_cvt_pk_bf16_f32 v2, v8, v9
	v_cvt_pk_bf16_f32 v3, v10, v11
	global_store_dwordx4 v[18:19], v[0:3], off
	s_cbranch_vccnz .LBB0_1115
	s_andn2_b64 vcc, exec, s[0:1]
	s_cbranch_vccnz .LBB0_1114
	s_barrier
	s_branch .LBB0_1114

; __device__ __forceinline__ unsigned cvtpk(float lo, float hi) { f32x2v_ v = {lo, hi}; bf16x2v_ b = __builtin_convertvector(v, bf16x2v_); return __builtin_bit_cast(unsigned, b); }
; __device__ __forceinline__ float row_rs(const float* ssp, int row) { const unsigned long long v = ((const unsigned long long*)ssp)[row];
;     return __builtin_amdgcn_rsqf((float)v * (1.0f / 4294967296.0f) * (1.0f / 1024.0f) + RMS_EPS); }
;     __device__ __forceinline__ void operator()(const f32x4 (&acc)[2][2][4][2], const Unit& u, int wr, int wc, int fr, int fq) const {
;     ...
;             for (int m = 0; m < 4; ++m) { const int row = row0 + ai * HALF + m * 16; const float rs = row_rs(ss, row);
;                 float hv[8];
; #pragma unroll
;                 for (int n = 0; n < 2; ++n)
; #pragma unroll
;                     for (int i = 0; i < 4; ++i) { const float g = acc[ai][0][m][n][i] * rs, uu = acc[ai][1][m][n][i] * rs;
;                         hv[n * 4 + i] = g * __builtin_amdgcn_rcpf(1.0f + __expf(-g)) * uu; }
;                 u32x4 w; w.x = cvtpk(hv[0], hv[1]); w.y = cvtpk(hv[2], hv[3]); w.z = cvtpk(hv[4], hv[5]); w.w = cvtpk(hv[6], hv[7]);
;                 *(u32x4*)(H + (size_t)row * ldh + col0) = w; }
.LBB0_1903:
	v_lshl_or_b32 v160, s52, 7, v154
	v_ashrrev_i32_e32 v161, 31, v160
	v_or_b32_e32 v164, 16, v144
	v_ashrrev_i32_e32 v165, 31, v164
	v_lshl_add_u64 v[166:167], v[164:165], 3, s[0:1]
	v_mov_b64_e32 v[146:147], s[20:21]
	v_mad_i64_i32 v[162:163], s[38:39], v144, s51, v[146:147]
	s_andn2_b64 vcc, exec, s[4:5]
	s_mov_b64 s[4:5], -1
	s_waitcnt vmcnt(7)
	v_cvt_f32_u32_e32 v159, v183
	v_cvt_f32_u32_e32 v145, v182
	v_lshlrev_b64 v[148:149], 1, v[160:161]
	v_lshl_add_u64 v[162:163], v[162:163], 0, v[148:149]
	v_fmamk_f32 v145, v145, 0x2f800000, v159
	v_fmamk_f32 v183, v145, 0x3a800000, v158
	v_rsq_f32_e32 v160, v183
	s_nop 0
	v_mul_f32_e32 v182, 0xbfb8aa3b, v160
	v_pk_mul_f32 v[160:161], v[124:125], v[182:183] op_sel_hi:[1,0]
	v_pk_mul_f32 v[168:169], v[126:127], v[182:183] op_sel_hi:[1,0]
	v_pk_mul_f32 v[170:171], v[120:121], v[182:183] op_sel_hi:[1,0]
	v_pk_mul_f32 v[172:173], v[122:123], v[182:183] op_sel_hi:[1,0]
	v_pk_mul_f32 v[116:117], v[116:117], v[124:125]
	v_pk_mul_f32 v[118:119], v[118:119], v[126:127]
	v_pk_mul_f32 v[120:121], v[112:113], v[120:121]
	v_pk_mul_f32 v[122:123], v[114:115], v[122:123]
	v_exp_f32_e32 v160, v160
	v_exp_f32_e32 v161, v161
	v_exp_f32_e32 v168, v168
	v_exp_f32_e32 v169, v169
	v_exp_f32_e32 v170, v170
	v_exp_f32_e32 v171, v171
	v_exp_f32_e32 v172, v172
	v_exp_f32_e32 v173, v173
	v_pk_fma_f32 v[160:161], v[160:161], v[182:183], v[182:183] op_sel:[0,1,1] op_sel_hi:[1,1,1]
	v_pk_fma_f32 v[168:169], v[168:169], v[182:183], v[182:183] op_sel:[0,1,1] op_sel_hi:[1,1,1]
	v_pk_fma_f32 v[170:171], v[170:171], v[182:183], v[182:183] op_sel:[0,1,1] op_sel_hi:[1,1,1]
	v_pk_fma_f32 v[172:173], v[172:173], v[182:183], v[182:183] op_sel:[0,1,1] op_sel_hi:[1,1,1]
	v_rcp_f32_e32 v160, v160
	v_rcp_f32_e32 v161, v161
	v_rcp_f32_e32 v168, v168
	v_rcp_f32_e32 v169, v169
	v_rcp_f32_e32 v170, v170
	v_rcp_f32_e32 v171, v171
	v_rcp_f32_e32 v172, v172
	v_rcp_f32_e32 v173, v173
	v_pk_mul_f32 v[116:117], v[116:117], v[160:161]
	v_pk_mul_f32 v[118:119], v[118:119], v[168:169]
	v_pk_mul_f32 v[120:121], v[120:121], v[170:171]
	v_pk_mul_f32 v[122:123], v[122:123], v[172:173]
	v_cvt_pk_bf16_f32 v112, v116, v117
	v_cvt_pk_bf16_f32 v113, v118, v119
	v_cvt_pk_bf16_f32 v114, v120, v121
	v_cvt_pk_bf16_f32 v115, v122, v123
	global_store_dwordx4 v[162:163], v[112:115], off
	s_nop 0
	s_nop 0
	v_or_b32_e32 v114, 32, v144
	s_waitcnt vmcnt(7)
	v_cvt_f32_u32_e32 v116, v185
	v_cvt_f32_u32_e32 v115, v184
	v_mad_i64_i32 v[112:113], s[38:39], v164, s51, v[146:147]
	v_fmamk_f32 v115, v115, 0x2f800000, v116
	v_fmamk_f32 v185, v115, 0x3a800000, v158
	v_rsq_f32_e32 v116, v185
	v_ashrrev_i32_e32 v115, 31, v114
	v_lshl_add_u64 v[118:119], v[114:115], 3, s[0:1]
	v_lshl_add_u64 v[112:113], v[112:113], 0, v[148:149]
	v_mul_f32_e32 v184, 0xbfb8aa3b, v116
	v_pk_mul_f32 v[116:117], v[108:109], v[184:185] op_sel_hi:[1,0]
	v_pk_mul_f32 v[120:121], v[110:111], v[184:185] op_sel_hi:[1,0]
	v_pk_mul_f32 v[122:123], v[104:105], v[184:185] op_sel_hi:[1,0]
	v_pk_mul_f32 v[124:125], v[106:107], v[184:185] op_sel_hi:[1,0]
	v_pk_mul_f32 v[100:101], v[100:101], v[108:109]
	v_pk_mul_f32 v[102:103], v[102:103], v[110:111]
	v_pk_mul_f32 v[104:105], v[96:97], v[104:105]
	v_pk_mul_f32 v[106:107], v[98:99], v[106:107]
	v_exp_f32_e32 v116, v116
	v_exp_f32_e32 v117, v117
	v_exp_f32_e32 v120, v120
	v_exp_f32_e32 v121, v121
	v_exp_f32_e32 v122, v122
	v_exp_f32_e32 v123, v123
	v_exp_f32_e32 v124, v124
	v_exp_f32_e32 v125, v125
	v_pk_fma_f32 v[116:117], v[116:117], v[184:185], v[184:185] op_sel:[0,1,1] op_sel_hi:[1,1,1]
	v_pk_fma_f32 v[120:121], v[120:121], v[184:185], v[184:185] op_sel:[0,1,1] op_sel_hi:[1,1,1]
	v_pk_fma_f32 v[122:123], v[122:123], v[184:185], v[184:185] op_sel:[0,1,1] op_sel_hi:[1,1,1]
	v_pk_fma_f32 v[124:125], v[124:125], v[184:185], v[184:185] op_sel:[0,1,1] op_sel_hi:[1,1,1]
	v_rcp_f32_e32 v116, v116
	v_rcp_f32_e32 v117, v117
	v_rcp_f32_e32 v120, v120
	v_rcp_f32_e32 v121, v121
	v_rcp_f32_e32 v122, v122
	v_rcp_f32_e32 v123, v123
	v_rcp_f32_e32 v124, v124
	v_rcp_f32_e32 v125, v125
	v_pk_mul_f32 v[100:101], v[100:101], v[116:117]
	v_pk_mul_f32 v[102:103], v[102:103], v[120:121]
	v_pk_mul_f32 v[104:105], v[104:105], v[122:123]
	v_pk_mul_f32 v[106:107], v[106:107], v[124:125]
	v_cvt_pk_bf16_f32 v96, v100, v101
	v_cvt_pk_bf16_f32 v97, v102, v103
	v_cvt_pk_bf16_f32 v98, v104, v105
	v_cvt_pk_bf16_f32 v99, v106, v107
	global_store_dwordx4 v[112:113], v[96:99], off
	s_nop 0
	s_nop 0
	v_or_b32_e32 v98, 48, v144
	s_waitcnt vmcnt(7)
	v_cvt_f32_u32_e32 v100, v187
	v_cvt_f32_u32_e32 v99, v186
	v_mad_i64_i32 v[96:97], s[38:39], v114, s51, v[146:147]
	v_fmamk_f32 v99, v99, 0x2f800000, v100
	v_fmamk_f32 v187, v99, 0x3a800000, v158
	v_rsq_f32_e32 v100, v187
	v_ashrrev_i32_e32 v99, 31, v98
	v_lshl_add_u64 v[102:103], v[98:99], 3, s[0:1]
	v_lshl_add_u64 v[96:97], v[96:97], 0, v[148:149]
	v_mul_f32_e32 v186, 0xbfb8aa3b, v100
	v_pk_mul_f32 v[100:101], v[92:93], v[186:187] op_sel_hi:[1,0]
	v_pk_mul_f32 v[104:105], v[94:95], v[186:187] op_sel_hi:[1,0]
	v_pk_mul_f32 v[106:107], v[88:89], v[186:187] op_sel_hi:[1,0]
	v_pk_mul_f32 v[108:109], v[90:91], v[186:187] op_sel_hi:[1,0]
	v_pk_mul_f32 v[84:85], v[84:85], v[92:93]
	v_pk_mul_f32 v[86:87], v[86:87], v[94:95]
	v_pk_mul_f32 v[88:89], v[80:81], v[88:89]
	v_pk_mul_f32 v[90:91], v[82:83], v[90:91]
	v_exp_f32_e32 v100, v100
	v_exp_f32_e32 v101, v101
	v_exp_f32_e32 v104, v104
	v_exp_f32_e32 v105, v105
	v_exp_f32_e32 v106, v106
	v_exp_f32_e32 v107, v107
	v_exp_f32_e32 v108, v108
	v_exp_f32_e32 v109, v109
	v_pk_fma_f32 v[100:101], v[100:101], v[186:187], v[186:187] op_sel:[0,1,1] op_sel_hi:[1,1,1]
	v_pk_fma_f32 v[104:105], v[104:105], v[186:187], v[186:187] op_sel:[0,1,1] op_sel_hi:[1,1,1]
	v_pk_fma_f32 v[106:107], v[106:107], v[186:187], v[186:187] op_sel:[0,1,1] op_sel_hi:[1,1,1]
	v_pk_fma_f32 v[108:109], v[108:109], v[186:187], v[186:187] op_sel:[0,1,1] op_sel_hi:[1,1,1]
	v_rcp_f32_e32 v100, v100
	v_rcp_f32_e32 v101, v101
	v_rcp_f32_e32 v104, v104
	v_rcp_f32_e32 v105, v105
	v_rcp_f32_e32 v106, v106
	v_rcp_f32_e32 v107, v107
	v_rcp_f32_e32 v108, v108
	v_rcp_f32_e32 v109, v109
	v_pk_mul_f32 v[84:85], v[84:85], v[100:101]
	v_pk_mul_f32 v[86:87], v[86:87], v[104:105]
	v_pk_mul_f32 v[88:89], v[88:89], v[106:107]
	v_pk_mul_f32 v[90:91], v[90:91], v[108:109]
	v_cvt_pk_bf16_f32 v80, v84, v85
	v_cvt_pk_bf16_f32 v81, v86, v87
	v_cvt_pk_bf16_f32 v82, v88, v89
	v_cvt_pk_bf16_f32 v83, v90, v91
	global_store_dwordx4 v[96:97], v[80:83], off
	s_nop 0
	s_waitcnt vmcnt(7)
; __device__ __forceinline__ unsigned cvtpk(float lo, float hi) { f32x2v_ v = {lo, hi}; bf16x2v_ b = __builtin_convertvector(v, bf16x2v_); return __builtin_bit_cast(unsigned, b); }
; __device__ __forceinline__ float row_rs(const float* ssp, int row) { const unsigned long long v = ((const unsigned long long*)ssp)[row];
;     return __builtin_amdgcn_rsqf((float)v * (1.0f / 4294967296.0f) * (1.0f / 1024.0f) + RMS_EPS); }
;     __device__ __forceinline__ void operator()(const f32x4 (&acc)[2][2][4][2], const Unit& u, int wr, int wc, int fr, int fq) const {
;     ...
;             for (int m = 0; m < 4; ++m) { const int row = row0 + ai * HALF + m * 16; const float rs = row_rs(ss, row);
;                 float hv[8];
; #pragma unroll
;                 for (int n = 0; n < 2; ++n)
; #pragma unroll
;                     for (int i = 0; i < 4; ++i) { const float g = acc[ai][0][m][n][i] * rs, uu = acc[ai][1][m][n][i] * rs;
;                         hv[n * 4 + i] = g * __builtin_amdgcn_rcpf(1.0f + __expf(-g)) * uu; }
;                 u32x4 w; w.x = cvtpk(hv[0], hv[1]); w.y = cvtpk(hv[2], hv[3]); w.z = cvtpk(hv[4], hv[5]); w.w = cvtpk(hv[6], hv[7]);
;                 *(u32x4*)(H + (size_t)row * ldh + col0) = w; }
	v_cvt_f32_u32_e32 v80, v189
	v_cvt_f32_u32_e32 v81, v188
	v_mad_i64_i32 v[82:83], s[38:39], v98, s51, v[146:147]
	v_fmamk_f32 v80, v81, 0x2f800000, v80
	v_fmamk_f32 v189, v80, 0x3a800000, v158
	v_rsq_f32_e32 v80, v189
	v_lshl_add_u64 v[82:83], v[82:83], 0, v[148:149]
	v_mul_f32_e32 v188, 0xbfb8aa3b, v80
	v_pk_mul_f32 v[80:81], v[76:77], v[188:189] op_sel_hi:[1,0]
	v_pk_mul_f32 v[84:85], v[78:79], v[188:189] op_sel_hi:[1,0]
	v_pk_mul_f32 v[86:87], v[72:73], v[188:189] op_sel_hi:[1,0]
	v_pk_mul_f32 v[88:89], v[74:75], v[188:189] op_sel_hi:[1,0]
	v_pk_mul_f32 v[68:69], v[68:69], v[76:77]
	v_pk_mul_f32 v[70:71], v[70:71], v[78:79]
	v_pk_mul_f32 v[72:73], v[64:65], v[72:73]
	v_pk_mul_f32 v[74:75], v[66:67], v[74:75]
	v_exp_f32_e32 v80, v80
	v_exp_f32_e32 v81, v81
	v_exp_f32_e32 v84, v84
	v_exp_f32_e32 v85, v85
	v_exp_f32_e32 v86, v86
	v_exp_f32_e32 v87, v87
	v_exp_f32_e32 v88, v88
	v_exp_f32_e32 v89, v89
	v_pk_fma_f32 v[80:81], v[80:81], v[188:189], v[188:189] op_sel:[0,1,1] op_sel_hi:[1,1,1]
	v_pk_fma_f32 v[84:85], v[84:85], v[188:189], v[188:189] op_sel:[0,1,1] op_sel_hi:[1,1,1]
	v_pk_fma_f32 v[86:87], v[86:87], v[188:189], v[188:189] op_sel:[0,1,1] op_sel_hi:[1,1,1]
	v_pk_fma_f32 v[88:89], v[88:89], v[188:189], v[188:189] op_sel:[0,1,1] op_sel_hi:[1,1,1]
	v_rcp_f32_e32 v80, v80
	v_rcp_f32_e32 v81, v81
	v_rcp_f32_e32 v84, v84
	v_rcp_f32_e32 v85, v85
	v_rcp_f32_e32 v86, v86
	v_rcp_f32_e32 v87, v87
	v_rcp_f32_e32 v88, v88
	v_rcp_f32_e32 v89, v89
	v_pk_mul_f32 v[68:69], v[68:69], v[80:81]
	v_pk_mul_f32 v[70:71], v[70:71], v[84:85]
	v_pk_mul_f32 v[72:73], v[72:73], v[86:87]
	v_pk_mul_f32 v[74:75], v[74:75], v[88:89]
	v_cvt_pk_bf16_f32 v64, v68, v69
	v_cvt_pk_bf16_f32 v65, v70, v71
	v_cvt_pk_bf16_f32 v66, v72, v73
	v_cvt_pk_bf16_f32 v67, v74, v75
	global_store_dwordx4 v[82:83], v[64:67], off
	s_nop 0
	s_waitcnt vmcnt(7)
	v_cvt_f32_u32_e32 v64, v191
	v_cvt_f32_u32_e32 v66, v190
	v_add_u32_e32 v65, 0x80, v144
	v_fmamk_f32 v64, v66, 0x2f800000, v64
	v_fmamk_f32 v191, v64, 0x3a800000, v158
	v_rsq_f32_e32 v64, v191
	v_mad_i64_i32 v[66:67], s[38:39], v65, s51, v[146:147]
	v_lshl_add_u64 v[66:67], v[66:67], 0, v[148:149]
	v_mul_f32_e32 v190, 0xbfb8aa3b, v64
	v_pk_mul_f32 v[64:65], v[60:61], v[190:191] op_sel_hi:[1,0]
	v_pk_mul_f32 v[68:69], v[62:63], v[190:191] op_sel_hi:[1,0]
	v_pk_mul_f32 v[70:71], v[56:57], v[190:191] op_sel_hi:[1,0]
	v_pk_mul_f32 v[72:73], v[58:59], v[190:191] op_sel_hi:[1,0]
	v_pk_mul_f32 v[52:53], v[52:53], v[60:61]
	v_pk_mul_f32 v[54:55], v[54:55], v[62:63]
	v_pk_mul_f32 v[56:57], v[48:49], v[56:57]
	v_pk_mul_f32 v[58:59], v[50:51], v[58:59]
	v_exp_f32_e32 v64, v64
	v_exp_f32_e32 v65, v65
	v_exp_f32_e32 v68, v68
	v_exp_f32_e32 v69, v69
	v_exp_f32_e32 v70, v70
	v_exp_f32_e32 v71, v71
	v_exp_f32_e32 v72, v72
	v_exp_f32_e32 v73, v73
	v_pk_fma_f32 v[64:65], v[64:65], v[190:191], v[190:191] op_sel:[0,1,1] op_sel_hi:[1,1,1]
	v_pk_fma_f32 v[68:69], v[68:69], v[190:191], v[190:191] op_sel:[0,1,1] op_sel_hi:[1,1,1]
	v_pk_fma_f32 v[70:71], v[70:71], v[190:191], v[190:191] op_sel:[0,1,1] op_sel_hi:[1,1,1]
	v_pk_fma_f32 v[72:73], v[72:73], v[190:191], v[190:191] op_sel:[0,1,1] op_sel_hi:[1,1,1]
	v_rcp_f32_e32 v64, v64
	v_rcp_f32_e32 v65, v65
	v_rcp_f32_e32 v68, v68
	v_rcp_f32_e32 v69, v69
	v_rcp_f32_e32 v70, v70
	v_rcp_f32_e32 v71, v71
	v_rcp_f32_e32 v72, v72
	v_rcp_f32_e32 v73, v73
	v_pk_mul_f32 v[52:53], v[52:53], v[64:65]
	v_pk_mul_f32 v[54:55], v[54:55], v[68:69]
	v_pk_mul_f32 v[56:57], v[56:57], v[70:71]
	v_pk_mul_f32 v[58:59], v[58:59], v[72:73]
	v_cvt_pk_bf16_f32 v48, v52, v53
	v_cvt_pk_bf16_f32 v49, v54, v55
	v_cvt_pk_bf16_f32 v50, v56, v57
	v_cvt_pk_bf16_f32 v51, v58, v59
	global_store_dwordx4 v[66:67], v[48:51], off
	s_nop 0
	s_waitcnt vmcnt(7)
	v_cvt_f32_u32_e32 v48, v193
	v_cvt_f32_u32_e32 v50, v192
	v_add_u32_e32 v49, 0x90, v144
	v_fmamk_f32 v48, v50, 0x2f800000, v48
	v_fmamk_f32 v193, v48, 0x3a800000, v158
	v_rsq_f32_e32 v48, v193
	v_mad_i64_i32 v[50:51], s[38:39], v49, s51, v[146:147]
	v_lshl_add_u64 v[50:51], v[50:51], 0, v[148:149]
	v_mul_f32_e32 v192, 0xbfb8aa3b, v48
	v_pk_mul_f32 v[48:49], v[44:45], v[192:193] op_sel_hi:[1,0]
	v_pk_mul_f32 v[52:53], v[46:47], v[192:193] op_sel_hi:[1,0]
	v_pk_mul_f32 v[54:55], v[40:41], v[192:193] op_sel_hi:[1,0]
	v_pk_mul_f32 v[56:57], v[42:43], v[192:193] op_sel_hi:[1,0]
	v_pk_mul_f32 v[36:37], v[36:37], v[44:45]
	v_pk_mul_f32 v[38:39], v[38:39], v[46:47]
	v_pk_mul_f32 v[40:41], v[32:33], v[40:41]
	v_pk_mul_f32 v[42:43], v[34:35], v[42:43]
	v_exp_f32_e32 v48, v48
	v_exp_f32_e32 v49, v49
	v_exp_f32_e32 v52, v52
	v_exp_f32_e32 v53, v53
	v_exp_f32_e32 v54, v54
	v_exp_f32_e32 v55, v55
	v_exp_f32_e32 v56, v56
	v_exp_f32_e32 v57, v57
	v_pk_fma_f32 v[48:49], v[48:49], v[192:193], v[192:193] op_sel:[0,1,1] op_sel_hi:[1,1,1]
	v_pk_fma_f32 v[52:53], v[52:53], v[192:193], v[192:193] op_sel:[0,1,1] op_sel_hi:[1,1,1]
	v_pk_fma_f32 v[54:55], v[54:55], v[192:193], v[192:193] op_sel:[0,1,1] op_sel_hi:[1,1,1]
	v_pk_fma_f32 v[56:57], v[56:57], v[192:193], v[192:193] op_sel:[0,1,1] op_sel_hi:[1,1,1]
	v_rcp_f32_e32 v48, v48
	v_rcp_f32_e32 v49, v49
	v_rcp_f32_e32 v52, v52
	v_rcp_f32_e32 v53, v53
	v_rcp_f32_e32 v54, v54
	v_rcp_f32_e32 v55, v55
	v_rcp_f32_e32 v56, v56
	v_rcp_f32_e32 v57, v57
	v_pk_mul_f32 v[36:37], v[36:37], v[48:49]
	v_pk_mul_f32 v[38:39], v[38:39], v[52:53]
	v_pk_mul_f32 v[40:41], v[40:41], v[54:55]
	v_pk_mul_f32 v[42:43], v[42:43], v[56:57]
	v_cvt_pk_bf16_f32 v32, v36, v37
	v_cvt_pk_bf16_f32 v33, v38, v39
	v_cvt_pk_bf16_f32 v34, v40, v41
	v_cvt_pk_bf16_f32 v35, v42, v43
	global_store_dwordx4 v[50:51], v[32:35], off
	s_nop 0
	s_waitcnt vmcnt(7)
; __device__ __forceinline__ unsigned cvtpk(float lo, float hi) { f32x2v_ v = {lo, hi}; bf16x2v_ b = __builtin_convertvector(v, bf16x2v_); return __builtin_bit_cast(unsigned, b); }
; __device__ __forceinline__ float row_rs(const float* ssp, int row) { const unsigned long long v = ((const unsigned long long*)ssp)[row];
;     return __builtin_amdgcn_rsqf((float)v * (1.0f / 4294967296.0f) * (1.0f / 1024.0f) + RMS_EPS); }
;     __device__ __forceinline__ void operator()(const f32x4 (&acc)[2][2][4][2], const Unit& u, int wr, int wc, int fr, int fq) const {
;     ...
;             for (int m = 0; m < 4; ++m) { const int row = row0 + ai * HALF + m * 16; const float rs = row_rs(ss, row);
;                 float hv[8];
; #pragma unroll
;                 for (int n = 0; n < 2; ++n)
; #pragma unroll
;                     for (int i = 0; i < 4; ++i) { const float g = acc[ai][0][m][n][i] * rs, uu = acc[ai][1][m][n][i] * rs;
;                         hv[n * 4 + i] = g * __builtin_amdgcn_rcpf(1.0f + __expf(-g)) * uu; }
;                 u32x4 w; w.x = cvtpk(hv[0], hv[1]); w.y = cvtpk(hv[2], hv[3]); w.z = cvtpk(hv[4], hv[5]); w.w = cvtpk(hv[6], hv[7]);
;                 *(u32x4*)(H + (size_t)row * ldh + col0) = w; }
	v_cvt_f32_u32_e32 v32, v195
	v_cvt_f32_u32_e32 v34, v194
	v_add_u32_e32 v33, 0xa0, v144
	v_fmamk_f32 v32, v34, 0x2f800000, v32
	v_fmamk_f32 v195, v32, 0x3a800000, v158
	v_rsq_f32_e32 v32, v195
	v_mad_i64_i32 v[34:35], s[38:39], v33, s51, v[146:147]
	v_lshl_add_u64 v[34:35], v[34:35], 0, v[148:149]
	v_mul_f32_e32 v194, 0xbfb8aa3b, v32
	v_pk_mul_f32 v[32:33], v[28:29], v[194:195] op_sel_hi:[1,0]
	v_pk_mul_f32 v[36:37], v[30:31], v[194:195] op_sel_hi:[1,0]
	v_pk_mul_f32 v[38:39], v[24:25], v[194:195] op_sel_hi:[1,0]
	v_pk_mul_f32 v[40:41], v[26:27], v[194:195] op_sel_hi:[1,0]
	v_pk_mul_f32 v[20:21], v[20:21], v[28:29]
	v_pk_mul_f32 v[22:23], v[22:23], v[30:31]
	v_pk_mul_f32 v[24:25], v[16:17], v[24:25]
	v_pk_mul_f32 v[26:27], v[18:19], v[26:27]
	v_exp_f32_e32 v32, v32
	v_exp_f32_e32 v33, v33
	v_exp_f32_e32 v36, v36
	v_exp_f32_e32 v37, v37
	v_exp_f32_e32 v38, v38
	v_exp_f32_e32 v39, v39
	v_exp_f32_e32 v40, v40
	v_exp_f32_e32 v41, v41
	v_pk_fma_f32 v[32:33], v[32:33], v[194:195], v[194:195] op_sel:[0,1,1] op_sel_hi:[1,1,1]
	v_pk_fma_f32 v[36:37], v[36:37], v[194:195], v[194:195] op_sel:[0,1,1] op_sel_hi:[1,1,1]
	v_pk_fma_f32 v[38:39], v[38:39], v[194:195], v[194:195] op_sel:[0,1,1] op_sel_hi:[1,1,1]
	v_pk_fma_f32 v[40:41], v[40:41], v[194:195], v[194:195] op_sel:[0,1,1] op_sel_hi:[1,1,1]
	v_rcp_f32_e32 v32, v32
	v_rcp_f32_e32 v33, v33
	v_rcp_f32_e32 v36, v36
	v_rcp_f32_e32 v37, v37
	v_rcp_f32_e32 v38, v38
	v_rcp_f32_e32 v39, v39
	v_rcp_f32_e32 v40, v40
	v_rcp_f32_e32 v41, v41
	v_pk_mul_f32 v[20:21], v[20:21], v[32:33]
	v_pk_mul_f32 v[22:23], v[22:23], v[36:37]
	v_pk_mul_f32 v[24:25], v[24:25], v[38:39]
	v_pk_mul_f32 v[26:27], v[26:27], v[40:41]
	v_cvt_pk_bf16_f32 v16, v20, v21
	v_cvt_pk_bf16_f32 v17, v22, v23
	v_cvt_pk_bf16_f32 v18, v24, v25
	v_cvt_pk_bf16_f32 v19, v26, v27
	global_store_dwordx4 v[34:35], v[16:19], off
	s_nop 0
	s_waitcnt vmcnt(7)
	v_cvt_f32_u32_e32 v16, v197
	v_cvt_f32_u32_e32 v18, v196
	v_add_u32_e32 v17, 0xb0, v144
	v_fmamk_f32 v16, v18, 0x2f800000, v16
	v_fmamk_f32 v197, v16, 0x3a800000, v158
	v_rsq_f32_e32 v16, v197
	v_mad_i64_i32 v[18:19], s[38:39], v17, s51, v[146:147]
	v_lshl_add_u64 v[18:19], v[18:19], 0, v[148:149]
	v_mul_f32_e32 v196, 0xbfb8aa3b, v16
	v_pk_mul_f32 v[16:17], v[12:13], v[196:197] op_sel_hi:[1,0]
	v_pk_mul_f32 v[20:21], v[14:15], v[196:197] op_sel_hi:[1,0]
	v_pk_mul_f32 v[22:23], v[8:9], v[196:197] op_sel_hi:[1,0]
	v_pk_mul_f32 v[24:25], v[10:11], v[196:197] op_sel_hi:[1,0]
	v_pk_mul_f32 v[4:5], v[4:5], v[12:13]
	v_pk_mul_f32 v[6:7], v[6:7], v[14:15]
	v_pk_mul_f32 v[8:9], v[0:1], v[8:9]
	v_pk_mul_f32 v[10:11], v[2:3], v[10:11]
	v_exp_f32_e32 v16, v16
	v_exp_f32_e32 v17, v17
	v_exp_f32_e32 v20, v20
	v_exp_f32_e32 v21, v21
	v_exp_f32_e32 v22, v22
	v_exp_f32_e32 v23, v23
	v_exp_f32_e32 v24, v24
	v_exp_f32_e32 v25, v25
	v_pk_fma_f32 v[16:17], v[16:17], v[196:197], v[196:197] op_sel:[0,1,1] op_sel_hi:[1,1,1]
	v_pk_fma_f32 v[20:21], v[20:21], v[196:197], v[196:197] op_sel:[0,1,1] op_sel_hi:[1,1,1]
	v_pk_fma_f32 v[22:23], v[22:23], v[196:197], v[196:197] op_sel:[0,1,1] op_sel_hi:[1,1,1]
	v_pk_fma_f32 v[24:25], v[24:25], v[196:197], v[196:197] op_sel:[0,1,1] op_sel_hi:[1,1,1]
	v_rcp_f32_e32 v16, v16
	v_rcp_f32_e32 v17, v17
	v_rcp_f32_e32 v20, v20
	v_rcp_f32_e32 v21, v21
	v_rcp_f32_e32 v22, v22
	v_rcp_f32_e32 v23, v23
	v_rcp_f32_e32 v24, v24
	v_rcp_f32_e32 v25, v25
	v_pk_mul_f32 v[4:5], v[4:5], v[16:17]
	v_pk_mul_f32 v[6:7], v[6:7], v[20:21]
	v_pk_mul_f32 v[8:9], v[8:9], v[22:23]
	v_pk_mul_f32 v[10:11], v[10:11], v[24:25]
	v_cvt_pk_bf16_f32 v0, v4, v5
	v_cvt_pk_bf16_f32 v1, v6, v7
	v_cvt_pk_bf16_f32 v2, v8, v9
	v_cvt_pk_bf16_f32 v3, v10, v11
	global_store_dwordx4 v[18:19], v[0:3], off
	s_cbranch_vccnz .LBB0_1896
	s_andn2_b64 vcc, exec, s[6:7]
	s_cbranch_vccnz .LBB0_1895
	s_barrier
	s_branch .LBB0_1895
